# mixers: diff-attention Q parking loads issued together, diff epilogue gain quads and GLU epilogue y/bias loads prefetched instead of one serialized load+store-ack wait per step
# speedup vs baseline: 1.0355x; 1.0027x over previous
.LBB0_453:
	s_add_u32 s12, s12, 0x1fa00600
	s_addc_u32 s13, s13, 0
	v_lshl_add_u32 v128, s19, 8, v138
	v_lshl_or_b32 v129, s28, 8, v139
	s_add_u32 s14, s10, 0x22a00000
	v_or_b32_e32 v132, s34, v129
	v_ashrrev_i32_e32 v129, 31, v128
	s_addc_u32 s15, s11, 0
	v_lshlrev_b64 v[130:131], 10, v[128:129]
	s_add_u32 s10, s16, s72
	v_lshl_add_u64 v[130:131], s[14:15], 0, v[130:131]
	v_lshlrev_b32_e32 v192, 1, v132
	s_addc_u32 s11, s17, s73
	v_lshl_add_u64 v[130:131], v[130:131], 0, v[192:193]
	v_lshlrev_b32_e32 v132, 2, v132
	v_mov_b64_e32 v[248:249], v[130:131]
	global_load_dwordx4 v[200:203], v132, s[10:11] offset:16
	global_load_dwordx4 v[204:207], v132, s[10:11]
	global_load_dwordx4 v[208:211], v132, s[10:11] offset:528
	global_load_dwordx4 v[240:243], v132, s[10:11] offset:512
	global_load_dwordx4 v[152:155], v[248:249], off
	global_load_dwordx4 v[156:159], v[248:249], off offset:256
	s_mov_b64 s[98:99], 0x4000
	v_lshl_add_u64 v[250:251], v[248:249], 0, s[98:99]
	global_load_dwordx4 v[160:163], v[250:251], off
	s_mov_b64 s[98:99], 0x4000
	v_lshl_add_u64 v[250:251], v[248:249], 0, s[98:99]
	global_load_dwordx4 v[164:167], v[250:251], off offset:256
	s_mov_b64 s[98:99], 0x8000
	v_lshl_add_u64 v[250:251], v[248:249], 0, s[98:99]
	global_load_dwordx4 v[168:171], v[250:251], off
	s_mov_b64 s[98:99], 0x8000
	v_lshl_add_u64 v[250:251], v[248:249], 0, s[98:99]
	global_load_dwordx4 v[172:175], v[250:251], off offset:256
	s_mov_b64 s[98:99], 0xc000
	v_lshl_add_u64 v[250:251], v[248:249], 0, s[98:99]
	global_load_dwordx4 v[176:179], v[250:251], off
	s_mov_b64 s[98:99], 0xc000
	v_lshl_add_u64 v[250:251], v[248:249], 0, s[98:99]
	global_load_dwordx4 v[180:183], v[250:251], off offset:256
	s_nop 1
	s_waitcnt vmcnt(7)
	v_mov_b64_e32 v[134:135], v[152:153]
	v_mov_b64_e32 v[136:137], v[154:155]
	v_mov_b64_e32 v[138:139], v[200:201]
	v_mov_b64_e32 v[140:141], v[202:203]
	v_mov_b64_e32 v[142:143], v[204:205]
	v_mov_b64_e32 v[144:145], v[206:207]
	v_add_f32_e32 v120, v120, v138
	v_add_f32_e32 v124, v124, v142
	v_add_f32_e32 v121, v121, v139
	v_add_f32_e32 v122, v122, v140
	v_mul_f32_e32 v124, 0xbfb8aa3b, v124
	v_mul_f32_e32 v120, 0xbfb8aa3b, v120
	v_mul_f32_e32 v121, 0xbfb8aa3b, v121
	v_mul_f32_e32 v122, 0xbfb8aa3b, v122
	v_exp_f32_e32 v124, v124
	v_exp_f32_e32 v120, v120
	v_exp_f32_e32 v121, v121
	v_exp_f32_e32 v122, v122
	v_add_f32_e32 v124, 1.0, v124
	v_add_f32_e32 v120, 1.0, v120
	v_add_f32_e32 v121, 1.0, v121
	v_add_f32_e32 v122, 1.0, v122
	v_rcp_f32_e32 v124, v124
	v_rcp_f32_e32 v120, v120
	v_rcp_f32_e32 v121, v121
	v_rcp_f32_e32 v122, v122
	v_lshlrev_b32_e32 v133, 16, v134
	v_lshlrev_b32_e32 v147, 16, v136
	v_and_b32_e32 v136, 0xffff0000, v136
	v_lshlrev_b32_e32 v148, 16, v137
	v_mul_f32_e32 v124, v124, v133
	v_mul_f32_e32 v133, v120, v147
	v_add_f32_e32 v120, v125, v143
	v_mul_f32_e32 v125, v121, v136
	v_add_f32_e32 v121, v126, v144
	v_mul_f32_e32 v126, v122, v148
	v_add_f32_e32 v122, v127, v145
	v_mul_f32_e32 v120, 0xbfb8aa3b, v120
	v_mul_f32_e32 v121, 0xbfb8aa3b, v121
	v_mul_f32_e32 v122, 0xbfb8aa3b, v122
	v_exp_f32_e32 v120, v120
	v_exp_f32_e32 v121, v121
	v_exp_f32_e32 v122, v122
	v_add_f32_e32 v123, v123, v141
	v_mul_f32_e32 v123, 0xbfb8aa3b, v123
	v_exp_f32_e32 v123, v123
	v_add_f32_e32 v120, 1.0, v120
	v_add_f32_e32 v121, 1.0, v121
	v_add_f32_e32 v122, 1.0, v122
	v_rcp_f32_e32 v120, v120
	v_rcp_f32_e32 v121, v121
	v_rcp_f32_e32 v122, v122
	v_add_f32_e32 v123, 1.0, v123
	v_and_b32_e32 v134, 0xffff0000, v134
	v_lshlrev_b32_e32 v146, 16, v135
	v_and_b32_e32 v135, 0xffff0000, v135
	v_rcp_f32_e32 v123, v123
	v_mul_f32_e32 v120, v120, v134
	v_mul_f32_e32 v121, v121, v146
	v_mul_f32_e32 v122, v122, v135
	v_cvt_pk_bf16_f32 v120, v124, v120
	v_cvt_pk_bf16_f32 v121, v121, v122
	v_cvt_pk_bf16_f32 v122, v133, v125
	v_lshlrev_b64 v[124:125], 12, v[128:129]
	v_and_b32_e32 v137, 0xffff0000, v137
	v_lshl_add_u64 v[124:125], s[12:13], 0, v[124:125]
	v_mul_f32_e32 v123, v123, v137
	v_lshl_add_u64 v[124:125], v[124:125], 0, v[192:193]
	v_cvt_pk_bf16_f32 v123, v126, v123
	global_store_dwordx4 v[124:125], v[120:123], off
	s_mov_b64 s[98:99], 0x20000
	v_lshl_add_u64 v[250:251], v[248:249], 0, s[98:99]
	global_load_dwordx4 v[152:155], v[250:251], off
	s_nop 1
	s_waitcnt vmcnt(8)
	v_mov_b64_e32 v[120:121], v[156:157]
	v_mov_b64_e32 v[122:123], v[158:159]
	s_nop 0
	v_mov_b64_e32 v[134:135], v[208:209]
	v_mov_b64_e32 v[136:137], v[210:211]
	v_mov_b64_e32 v[138:139], v[240:241]
	v_mov_b64_e32 v[140:141], v[242:243]
	v_lshlrev_b32_e32 v126, 16, v120
	v_add_f32_e32 v112, v112, v134
	v_add_f32_e32 v116, v116, v138
	v_add_f32_e32 v113, v113, v135
	v_add_f32_e32 v114, v114, v136
	v_mul_f32_e32 v116, 0xbfb8aa3b, v116
	v_mul_f32_e32 v112, 0xbfb8aa3b, v112
	v_mul_f32_e32 v113, 0xbfb8aa3b, v113
	v_mul_f32_e32 v114, 0xbfb8aa3b, v114
	v_exp_f32_e32 v116, v116
	v_exp_f32_e32 v112, v112
	v_exp_f32_e32 v113, v113
	v_exp_f32_e32 v114, v114
	v_add_f32_e32 v116, 1.0, v116
	v_add_f32_e32 v112, 1.0, v112
	v_add_f32_e32 v113, 1.0, v113
	v_add_f32_e32 v114, 1.0, v114
	v_rcp_f32_e32 v116, v116
	v_rcp_f32_e32 v112, v112
	v_rcp_f32_e32 v113, v113
	v_rcp_f32_e32 v114, v114
	v_lshlrev_b32_e32 v129, 16, v122
	v_and_b32_e32 v122, 0xffff0000, v122
	v_lshlrev_b32_e32 v130, 16, v123
	v_mul_f32_e32 v116, v116, v126
	v_mul_f32_e32 v126, v112, v129
	v_add_f32_e32 v112, v117, v139
	v_mul_f32_e32 v117, v113, v122
	v_add_f32_e32 v113, v118, v140
	v_mul_f32_e32 v118, v114, v130
	v_add_f32_e32 v114, v119, v141
	v_mul_f32_e32 v112, 0xbfb8aa3b, v112
	v_mul_f32_e32 v113, 0xbfb8aa3b, v113
	v_add_f32_e32 v115, v115, v137
	v_mul_f32_e32 v114, 0xbfb8aa3b, v114
	v_exp_f32_e32 v112, v112
	v_exp_f32_e32 v113, v113
	v_exp_f32_e32 v114, v114
	v_mul_f32_e32 v115, 0xbfb8aa3b, v115
	v_exp_f32_e32 v115, v115
	v_add_f32_e32 v112, 1.0, v112
	v_add_f32_e32 v113, 1.0, v113
	v_add_f32_e32 v114, 1.0, v114
	v_rcp_f32_e32 v112, v112
	v_rcp_f32_e32 v113, v113
	v_rcp_f32_e32 v114, v114
	v_add_f32_e32 v115, 1.0, v115
	v_rcp_f32_e32 v115, v115
	v_and_b32_e32 v120, 0xffff0000, v120
	v_lshlrev_b32_e32 v127, 16, v121
	v_and_b32_e32 v121, 0xffff0000, v121
	v_and_b32_e32 v123, 0xffff0000, v123
	v_mul_f32_e32 v112, v112, v120
	v_mul_f32_e32 v113, v113, v127
	v_mul_f32_e32 v114, v114, v121
	v_mul_f32_e32 v115, v115, v123
	v_cvt_pk_bf16_f32 v112, v116, v112
	v_cvt_pk_bf16_f32 v113, v113, v114
	v_cvt_pk_bf16_f32 v114, v126, v117
	v_cvt_pk_bf16_f32 v115, v118, v115
	global_store_dwordx4 v[124:125], v[112:115], off offset:256
	s_mov_b64 s[98:99], 0x20000
	v_lshl_add_u64 v[250:251], v[248:249], 0, s[98:99]
	global_load_dwordx4 v[156:159], v[250:251], off offset:256
	s_nop 1
	v_or_b32_e32 v114, 16, v128
	v_ashrrev_i32_e32 v115, 31, v114
	v_lshlrev_b64 v[112:113], 10, v[114:115]
	v_lshl_add_u64 v[112:113], s[14:15], 0, v[112:113]
	v_lshl_add_u64 v[112:113], v[112:113], 0, v[192:193]
	s_nop 1
	s_waitcnt vmcnt(9)
	v_mov_b64_e32 v[116:117], v[160:161]
	v_mov_b64_e32 v[118:119], v[162:163]
	v_mov_b64_e32 v[120:121], v[200:201]
	v_mov_b64_e32 v[122:123], v[202:203]
	v_mov_b64_e32 v[124:125], v[204:205]
	v_mov_b64_e32 v[126:127], v[206:207]
	v_lshlrev_b32_e32 v131, 16, v118
	v_add_f32_e32 v104, v104, v120
	v_add_f32_e32 v105, v105, v121
	v_add_f32_e32 v106, v106, v122
	v_mul_f32_e32 v104, 0xbfb8aa3b, v104
	v_mul_f32_e32 v105, 0xbfb8aa3b, v105
	v_mul_f32_e32 v106, 0xbfb8aa3b, v106
	v_exp_f32_e32 v104, v104
	v_exp_f32_e32 v105, v105
	v_exp_f32_e32 v106, v106
	v_and_b32_e32 v118, 0xffff0000, v118
	v_add_f32_e32 v104, 1.0, v104
	v_add_f32_e32 v105, 1.0, v105
	v_add_f32_e32 v106, 1.0, v106
	v_rcp_f32_e32 v104, v104
	v_rcp_f32_e32 v105, v105
	v_rcp_f32_e32 v106, v106
	v_lshlrev_b32_e32 v133, 16, v119
	v_add_f32_e32 v108, v108, v124
	v_mul_f32_e32 v120, v104, v131
	v_add_f32_e32 v104, v109, v125
	v_mul_f32_e32 v109, v105, v118
	v_add_f32_e32 v105, v110, v126
	v_mul_f32_e32 v110, v106, v133
	v_add_f32_e32 v106, v111, v127
	v_mul_f32_e32 v108, 0xbfb8aa3b, v108
	v_mul_f32_e32 v104, 0xbfb8aa3b, v104
	v_mul_f32_e32 v105, 0xbfb8aa3b, v105
	v_mul_f32_e32 v106, 0xbfb8aa3b, v106
	v_exp_f32_e32 v108, v108
	v_exp_f32_e32 v104, v104
	v_exp_f32_e32 v105, v105
	v_exp_f32_e32 v106, v106
	v_add_f32_e32 v107, v107, v123
	v_mul_f32_e32 v107, 0xbfb8aa3b, v107
	v_exp_f32_e32 v107, v107
	v_add_f32_e32 v108, 1.0, v108
	v_add_f32_e32 v104, 1.0, v104
	v_add_f32_e32 v105, 1.0, v105
	v_add_f32_e32 v106, 1.0, v106
	v_rcp_f32_e32 v108, v108
	v_rcp_f32_e32 v104, v104
	v_rcp_f32_e32 v105, v105
	v_rcp_f32_e32 v106, v106
	v_add_f32_e32 v107, 1.0, v107
	v_lshlrev_b32_e32 v129, 16, v116
	v_and_b32_e32 v116, 0xffff0000, v116
	v_lshlrev_b32_e32 v130, 16, v117
	v_and_b32_e32 v117, 0xffff0000, v117
	v_rcp_f32_e32 v107, v107
	v_mul_f32_e32 v108, v108, v129
	v_mul_f32_e32 v104, v104, v116
	v_mul_f32_e32 v105, v105, v130
	v_mul_f32_e32 v106, v106, v117
	v_cvt_pk_bf16_f32 v104, v108, v104
	v_cvt_pk_bf16_f32 v105, v105, v106
	v_cvt_pk_bf16_f32 v106, v120, v109
	v_lshlrev_b64 v[108:109], 12, v[114:115]
	v_and_b32_e32 v119, 0xffff0000, v119
	v_lshl_add_u64 v[108:109], s[12:13], 0, v[108:109]
	v_mul_f32_e32 v107, v107, v119
	v_lshl_add_u64 v[108:109], v[108:109], 0, v[192:193]
	v_cvt_pk_bf16_f32 v107, v110, v107
	global_store_dwordx4 v[108:109], v[104:107], off
	s_mov_b64 s[98:99], 0x24000
	v_lshl_add_u64 v[250:251], v[248:249], 0, s[98:99]
	global_load_dwordx4 v[160:163], v[250:251], off
	s_nop 1
	s_waitcnt vmcnt(10)
	v_mov_b64_e32 v[104:105], v[164:165]
	v_mov_b64_e32 v[106:107], v[166:167]
	s_nop 0
	v_mov_b64_e32 v[110:111], v[208:209]
	v_mov_b64_e32 v[112:113], v[210:211]
	v_mov_b64_e32 v[114:115], v[240:241]
	v_mov_b64_e32 v[116:117], v[242:243]
	v_lshlrev_b32_e32 v120, 16, v106
	v_add_f32_e32 v96, v96, v110
	v_add_f32_e32 v97, v97, v111
	v_add_f32_e32 v98, v98, v112
	v_mul_f32_e32 v96, 0xbfb8aa3b, v96
	v_mul_f32_e32 v97, 0xbfb8aa3b, v97
	v_mul_f32_e32 v98, 0xbfb8aa3b, v98
	v_exp_f32_e32 v96, v96
	v_exp_f32_e32 v97, v97
	v_exp_f32_e32 v98, v98
	v_and_b32_e32 v106, 0xffff0000, v106
	v_add_f32_e32 v96, 1.0, v96
	v_add_f32_e32 v97, 1.0, v97
	v_add_f32_e32 v98, 1.0, v98
	v_rcp_f32_e32 v96, v96
	v_rcp_f32_e32 v97, v97
	v_rcp_f32_e32 v98, v98
	v_lshlrev_b32_e32 v121, 16, v107
	v_mul_f32_e32 v110, v96, v120
	v_add_f32_e32 v96, v101, v115
	v_mul_f32_e32 v101, v97, v106
	v_add_f32_e32 v97, v102, v116
	v_mul_f32_e32 v102, v98, v121
	v_add_f32_e32 v98, v103, v117
	v_add_f32_e32 v100, v100, v114
	v_mul_f32_e32 v96, 0xbfb8aa3b, v96
	v_mul_f32_e32 v97, 0xbfb8aa3b, v97
	v_add_f32_e32 v99, v99, v113
	v_mul_f32_e32 v98, 0xbfb8aa3b, v98
	v_mul_f32_e32 v100, 0xbfb8aa3b, v100
	v_exp_f32_e32 v96, v96
	v_exp_f32_e32 v97, v97
	v_exp_f32_e32 v98, v98
	v_mul_f32_e32 v99, 0xbfb8aa3b, v99
	v_exp_f32_e32 v100, v100
	v_exp_f32_e32 v99, v99
	v_add_f32_e32 v96, 1.0, v96
	v_add_f32_e32 v97, 1.0, v97
	v_add_f32_e32 v98, 1.0, v98
	v_add_f32_e32 v100, 1.0, v100
	v_rcp_f32_e32 v96, v96
	v_rcp_f32_e32 v97, v97
	v_rcp_f32_e32 v98, v98
	v_add_f32_e32 v99, 1.0, v99
	v_rcp_f32_e32 v100, v100
	v_rcp_f32_e32 v99, v99
	v_lshlrev_b32_e32 v118, 16, v104
	v_and_b32_e32 v104, 0xffff0000, v104
	v_lshlrev_b32_e32 v119, 16, v105
	v_and_b32_e32 v105, 0xffff0000, v105
	v_and_b32_e32 v107, 0xffff0000, v107
	v_mul_f32_e32 v96, v96, v104
	v_mul_f32_e32 v97, v97, v119
	v_mul_f32_e32 v98, v98, v105
	v_mul_f32_e32 v100, v100, v118
	v_mul_f32_e32 v99, v99, v107
	v_cvt_pk_bf16_f32 v96, v100, v96
	v_cvt_pk_bf16_f32 v97, v97, v98
	v_cvt_pk_bf16_f32 v98, v110, v101
	v_cvt_pk_bf16_f32 v99, v102, v99
	global_store_dwordx4 v[108:109], v[96:99], off offset:256
	s_mov_b64 s[98:99], 0x24000
	v_lshl_add_u64 v[250:251], v[248:249], 0, s[98:99]
	global_load_dwordx4 v[164:167], v[250:251], off offset:256
	s_nop 1
	v_or_b32_e32 v98, 32, v128
	v_ashrrev_i32_e32 v99, 31, v98
	v_lshlrev_b64 v[96:97], 10, v[98:99]
	v_lshl_add_u64 v[96:97], s[14:15], 0, v[96:97]
	v_lshl_add_u64 v[96:97], v[96:97], 0, v[192:193]
	s_nop 1
	s_waitcnt vmcnt(11)
	v_mov_b64_e32 v[100:101], v[168:169]
	v_mov_b64_e32 v[102:103], v[170:171]
	v_mov_b64_e32 v[104:105], v[200:201]
	v_mov_b64_e32 v[106:107], v[202:203]
	v_mov_b64_e32 v[108:109], v[204:205]
	v_mov_b64_e32 v[110:111], v[206:207]
	v_lshlrev_b32_e32 v114, 16, v102
	v_add_f32_e32 v88, v88, v104
	v_add_f32_e32 v89, v89, v105
	v_add_f32_e32 v90, v90, v106
	v_mul_f32_e32 v88, 0xbfb8aa3b, v88
	v_mul_f32_e32 v89, 0xbfb8aa3b, v89
	v_mul_f32_e32 v90, 0xbfb8aa3b, v90
	v_exp_f32_e32 v88, v88
	v_exp_f32_e32 v89, v89
	v_exp_f32_e32 v90, v90
	v_and_b32_e32 v102, 0xffff0000, v102
	v_add_f32_e32 v88, 1.0, v88
	v_add_f32_e32 v89, 1.0, v89
	v_add_f32_e32 v90, 1.0, v90
	v_rcp_f32_e32 v88, v88
	v_rcp_f32_e32 v89, v89
	v_rcp_f32_e32 v90, v90
	v_lshlrev_b32_e32 v115, 16, v103
	v_add_f32_e32 v92, v92, v108
	v_mul_f32_e32 v104, v88, v114
	v_add_f32_e32 v88, v93, v109
	v_mul_f32_e32 v93, v89, v102
	v_add_f32_e32 v89, v94, v110
	v_mul_f32_e32 v94, v90, v115
	v_add_f32_e32 v90, v95, v111
	v_mul_f32_e32 v92, 0xbfb8aa3b, v92
	v_mul_f32_e32 v88, 0xbfb8aa3b, v88
	v_mul_f32_e32 v89, 0xbfb8aa3b, v89
	v_mul_f32_e32 v90, 0xbfb8aa3b, v90
	v_exp_f32_e32 v92, v92
	v_exp_f32_e32 v88, v88
	v_exp_f32_e32 v89, v89
	v_exp_f32_e32 v90, v90
	v_add_f32_e32 v91, v91, v107
	v_mul_f32_e32 v91, 0xbfb8aa3b, v91
	v_exp_f32_e32 v91, v91
	v_add_f32_e32 v92, 1.0, v92
	v_add_f32_e32 v88, 1.0, v88
	v_add_f32_e32 v89, 1.0, v89
	v_add_f32_e32 v90, 1.0, v90
	v_rcp_f32_e32 v92, v92
	v_rcp_f32_e32 v88, v88
	v_rcp_f32_e32 v89, v89
	v_rcp_f32_e32 v90, v90
	v_add_f32_e32 v91, 1.0, v91
	v_lshlrev_b32_e32 v112, 16, v100
	v_and_b32_e32 v100, 0xffff0000, v100
	v_lshlrev_b32_e32 v113, 16, v101
	v_and_b32_e32 v101, 0xffff0000, v101
	v_rcp_f32_e32 v91, v91
	v_mul_f32_e32 v92, v92, v112
	v_mul_f32_e32 v88, v88, v100
	v_mul_f32_e32 v89, v89, v113
	v_mul_f32_e32 v90, v90, v101
	v_cvt_pk_bf16_f32 v88, v92, v88
	v_cvt_pk_bf16_f32 v89, v89, v90
	v_cvt_pk_bf16_f32 v90, v104, v93
	v_lshlrev_b64 v[92:93], 12, v[98:99]
	v_and_b32_e32 v103, 0xffff0000, v103
	v_lshl_add_u64 v[92:93], s[12:13], 0, v[92:93]
	v_mul_f32_e32 v91, v91, v103
	v_lshl_add_u64 v[92:93], v[92:93], 0, v[192:193]
	v_cvt_pk_bf16_f32 v91, v94, v91
	global_store_dwordx4 v[92:93], v[88:91], off
	s_mov_b64 s[98:99], 0x28000
	v_lshl_add_u64 v[250:251], v[248:249], 0, s[98:99]
	global_load_dwordx4 v[168:171], v[250:251], off
	s_nop 1
	s_waitcnt vmcnt(12)
	v_mov_b64_e32 v[88:89], v[172:173]
	v_mov_b64_e32 v[90:91], v[174:175]
	s_nop 0
	v_mov_b64_e32 v[94:95], v[208:209]
	v_mov_b64_e32 v[96:97], v[210:211]
	v_mov_b64_e32 v[98:99], v[240:241]
	v_mov_b64_e32 v[100:101], v[242:243]
	v_lshlrev_b32_e32 v104, 16, v90
	v_add_f32_e32 v80, v80, v94
	v_add_f32_e32 v81, v81, v95
	v_add_f32_e32 v82, v82, v96
	v_mul_f32_e32 v80, 0xbfb8aa3b, v80
	v_mul_f32_e32 v81, 0xbfb8aa3b, v81
	v_mul_f32_e32 v82, 0xbfb8aa3b, v82
	v_exp_f32_e32 v80, v80
	v_exp_f32_e32 v81, v81
	v_exp_f32_e32 v82, v82
	v_and_b32_e32 v90, 0xffff0000, v90
	v_add_f32_e32 v80, 1.0, v80
	v_add_f32_e32 v81, 1.0, v81
	v_add_f32_e32 v82, 1.0, v82
	v_rcp_f32_e32 v80, v80
	v_rcp_f32_e32 v81, v81
	v_rcp_f32_e32 v82, v82
	v_lshlrev_b32_e32 v105, 16, v91
	v_mul_f32_e32 v94, v80, v104
	v_add_f32_e32 v80, v85, v99
	v_mul_f32_e32 v85, v81, v90
	v_add_f32_e32 v81, v86, v100
	v_mul_f32_e32 v86, v82, v105
	v_add_f32_e32 v82, v87, v101
	v_add_f32_e32 v84, v84, v98
	v_mul_f32_e32 v80, 0xbfb8aa3b, v80
	v_mul_f32_e32 v81, 0xbfb8aa3b, v81
	v_add_f32_e32 v83, v83, v97
	v_mul_f32_e32 v82, 0xbfb8aa3b, v82
	v_mul_f32_e32 v84, 0xbfb8aa3b, v84
	v_exp_f32_e32 v80, v80
	v_exp_f32_e32 v81, v81
	v_exp_f32_e32 v82, v82
	v_mul_f32_e32 v83, 0xbfb8aa3b, v83
	v_exp_f32_e32 v84, v84
	v_exp_f32_e32 v83, v83
	v_add_f32_e32 v80, 1.0, v80
	v_add_f32_e32 v81, 1.0, v81
	v_add_f32_e32 v82, 1.0, v82
	v_add_f32_e32 v84, 1.0, v84
	v_rcp_f32_e32 v80, v80
	v_rcp_f32_e32 v81, v81
	v_rcp_f32_e32 v82, v82
	v_add_f32_e32 v83, 1.0, v83
	v_rcp_f32_e32 v84, v84
	v_rcp_f32_e32 v83, v83
	v_lshlrev_b32_e32 v102, 16, v88
	v_and_b32_e32 v88, 0xffff0000, v88
	v_lshlrev_b32_e32 v103, 16, v89
	v_and_b32_e32 v89, 0xffff0000, v89
	v_and_b32_e32 v91, 0xffff0000, v91
	v_mul_f32_e32 v80, v80, v88
	v_mul_f32_e32 v81, v81, v103
	v_mul_f32_e32 v82, v82, v89
	v_mul_f32_e32 v84, v84, v102
	v_mul_f32_e32 v83, v83, v91
	v_cvt_pk_bf16_f32 v80, v84, v80
	v_cvt_pk_bf16_f32 v81, v81, v82
	v_cvt_pk_bf16_f32 v82, v94, v85
	v_cvt_pk_bf16_f32 v83, v86, v83
	global_store_dwordx4 v[92:93], v[80:83], off offset:256
	s_mov_b64 s[98:99], 0x28000
	v_lshl_add_u64 v[250:251], v[248:249], 0, s[98:99]
	global_load_dwordx4 v[172:175], v[250:251], off offset:256
	s_nop 1
	v_or_b32_e32 v82, 48, v128
	v_ashrrev_i32_e32 v83, 31, v82
	v_lshlrev_b64 v[80:81], 10, v[82:83]
	v_lshl_add_u64 v[80:81], s[14:15], 0, v[80:81]
	v_lshl_add_u64 v[80:81], v[80:81], 0, v[192:193]
	s_nop 1
	s_waitcnt vmcnt(13)
	v_mov_b64_e32 v[84:85], v[176:177]
	v_mov_b64_e32 v[86:87], v[178:179]
	v_mov_b64_e32 v[88:89], v[200:201]
	v_mov_b64_e32 v[90:91], v[202:203]
	v_mov_b64_e32 v[92:93], v[204:205]
	v_mov_b64_e32 v[94:95], v[206:207]
	v_lshlrev_b32_e32 v98, 16, v86
	v_add_f32_e32 v72, v72, v88
	v_add_f32_e32 v73, v73, v89
	v_add_f32_e32 v74, v74, v90
	v_mul_f32_e32 v72, 0xbfb8aa3b, v72
	v_mul_f32_e32 v73, 0xbfb8aa3b, v73
	v_mul_f32_e32 v74, 0xbfb8aa3b, v74
	v_exp_f32_e32 v72, v72
	v_exp_f32_e32 v73, v73
	v_exp_f32_e32 v74, v74
	v_and_b32_e32 v86, 0xffff0000, v86
	v_add_f32_e32 v72, 1.0, v72
	v_add_f32_e32 v73, 1.0, v73
	v_add_f32_e32 v74, 1.0, v74
	v_rcp_f32_e32 v72, v72
	v_rcp_f32_e32 v73, v73
	v_rcp_f32_e32 v74, v74
	v_lshlrev_b32_e32 v99, 16, v87
	v_add_f32_e32 v76, v76, v92
	v_mul_f32_e32 v88, v72, v98
	v_add_f32_e32 v72, v77, v93
	v_mul_f32_e32 v77, v73, v86
	v_add_f32_e32 v73, v78, v94
	v_mul_f32_e32 v78, v74, v99
	v_add_f32_e32 v74, v79, v95
	v_mul_f32_e32 v76, 0xbfb8aa3b, v76
	v_mul_f32_e32 v72, 0xbfb8aa3b, v72
	v_mul_f32_e32 v73, 0xbfb8aa3b, v73
	v_mul_f32_e32 v74, 0xbfb8aa3b, v74
	v_exp_f32_e32 v76, v76
	v_exp_f32_e32 v72, v72
	v_exp_f32_e32 v73, v73
	v_exp_f32_e32 v74, v74
	v_add_f32_e32 v75, v75, v91
	v_mul_f32_e32 v75, 0xbfb8aa3b, v75
	v_exp_f32_e32 v75, v75
	v_add_f32_e32 v76, 1.0, v76
	v_add_f32_e32 v72, 1.0, v72
	v_add_f32_e32 v73, 1.0, v73
	v_add_f32_e32 v74, 1.0, v74
	v_rcp_f32_e32 v76, v76
	v_rcp_f32_e32 v72, v72
	v_rcp_f32_e32 v73, v73
	v_rcp_f32_e32 v74, v74
	v_add_f32_e32 v75, 1.0, v75
	v_lshlrev_b32_e32 v96, 16, v84
	v_and_b32_e32 v84, 0xffff0000, v84
	v_lshlrev_b32_e32 v97, 16, v85
	v_and_b32_e32 v85, 0xffff0000, v85
	v_rcp_f32_e32 v75, v75
	v_mul_f32_e32 v76, v76, v96
	v_mul_f32_e32 v72, v72, v84
	v_mul_f32_e32 v73, v73, v97
	v_mul_f32_e32 v74, v74, v85
	v_cvt_pk_bf16_f32 v72, v76, v72
	v_cvt_pk_bf16_f32 v73, v73, v74
	v_cvt_pk_bf16_f32 v74, v88, v77
	v_lshlrev_b64 v[76:77], 12, v[82:83]
	v_and_b32_e32 v87, 0xffff0000, v87
	v_lshl_add_u64 v[76:77], s[12:13], 0, v[76:77]
	v_mul_f32_e32 v75, v75, v87
	v_lshl_add_u64 v[76:77], v[76:77], 0, v[192:193]
	v_cvt_pk_bf16_f32 v75, v78, v75
	global_store_dwordx4 v[76:77], v[72:75], off
	s_mov_b64 s[98:99], 0x2c000
	v_lshl_add_u64 v[250:251], v[248:249], 0, s[98:99]
	global_load_dwordx4 v[176:179], v[250:251], off
	s_nop 1
	s_waitcnt vmcnt(14)
	v_mov_b64_e32 v[72:73], v[180:181]
	v_mov_b64_e32 v[74:75], v[182:183]
	s_nop 0
	v_mov_b64_e32 v[78:79], v[208:209]
	v_mov_b64_e32 v[80:81], v[210:211]
	v_mov_b64_e32 v[82:83], v[240:241]
	v_mov_b64_e32 v[84:85], v[242:243]
	v_lshlrev_b32_e32 v88, 16, v74
	v_add_f32_e32 v64, v64, v78
	v_add_f32_e32 v65, v65, v79
	v_add_f32_e32 v66, v66, v80
	v_mul_f32_e32 v64, 0xbfb8aa3b, v64
	v_mul_f32_e32 v65, 0xbfb8aa3b, v65
	v_mul_f32_e32 v66, 0xbfb8aa3b, v66
	v_exp_f32_e32 v64, v64
	v_exp_f32_e32 v65, v65
	v_exp_f32_e32 v66, v66
	v_and_b32_e32 v74, 0xffff0000, v74
	v_add_f32_e32 v64, 1.0, v64
	v_add_f32_e32 v65, 1.0, v65
	v_add_f32_e32 v66, 1.0, v66
	v_rcp_f32_e32 v64, v64
	v_rcp_f32_e32 v65, v65
	v_rcp_f32_e32 v66, v66
	v_lshlrev_b32_e32 v89, 16, v75
	v_mul_f32_e32 v78, v64, v88
	v_add_f32_e32 v64, v69, v83
	v_mul_f32_e32 v69, v65, v74
	v_add_f32_e32 v65, v70, v84
	v_mul_f32_e32 v70, v66, v89
	v_add_f32_e32 v66, v71, v85
	v_add_f32_e32 v68, v68, v82
	v_mul_f32_e32 v64, 0xbfb8aa3b, v64
	v_mul_f32_e32 v65, 0xbfb8aa3b, v65
	v_add_f32_e32 v67, v67, v81
	v_mul_f32_e32 v66, 0xbfb8aa3b, v66
	v_mul_f32_e32 v68, 0xbfb8aa3b, v68
	v_exp_f32_e32 v64, v64
	v_exp_f32_e32 v65, v65
	v_exp_f32_e32 v66, v66
	v_mul_f32_e32 v67, 0xbfb8aa3b, v67
	v_exp_f32_e32 v68, v68
	v_exp_f32_e32 v67, v67
	v_add_f32_e32 v64, 1.0, v64
	v_add_f32_e32 v65, 1.0, v65
	v_add_f32_e32 v66, 1.0, v66
	v_add_f32_e32 v68, 1.0, v68
	v_rcp_f32_e32 v64, v64
	v_rcp_f32_e32 v65, v65
	v_rcp_f32_e32 v66, v66
	v_add_f32_e32 v67, 1.0, v67
	v_rcp_f32_e32 v68, v68
	v_rcp_f32_e32 v67, v67
	v_lshlrev_b32_e32 v86, 16, v72
	v_and_b32_e32 v72, 0xffff0000, v72
	v_lshlrev_b32_e32 v87, 16, v73
	v_and_b32_e32 v73, 0xffff0000, v73
	v_and_b32_e32 v75, 0xffff0000, v75
	v_mul_f32_e32 v64, v64, v72
	v_mul_f32_e32 v65, v65, v87
	v_mul_f32_e32 v66, v66, v73
	v_mul_f32_e32 v68, v68, v86
	v_mul_f32_e32 v67, v67, v75
	v_cvt_pk_bf16_f32 v64, v68, v64
	v_cvt_pk_bf16_f32 v65, v65, v66
	v_cvt_pk_bf16_f32 v66, v78, v69
	v_cvt_pk_bf16_f32 v67, v70, v67
	global_store_dwordx4 v[76:77], v[64:67], off offset:256
	s_mov_b64 s[98:99], 0x2c000
	v_lshl_add_u64 v[250:251], v[248:249], 0, s[98:99]
	global_load_dwordx4 v[180:183], v[250:251], off offset:256
	s_nop 1
	v_add_u32_e32 v66, 0x80, v128
	v_ashrrev_i32_e32 v67, 31, v66
	v_lshlrev_b64 v[64:65], 10, v[66:67]
	v_lshl_add_u64 v[64:65], s[14:15], 0, v[64:65]
	v_lshl_add_u64 v[64:65], v[64:65], 0, v[192:193]
	s_nop 1
	s_waitcnt vmcnt(14)
	v_mov_b64_e32 v[68:69], v[152:153]
	v_mov_b64_e32 v[70:71], v[154:155]
	v_mov_b64_e32 v[72:73], v[200:201]
	v_mov_b64_e32 v[74:75], v[202:203]
	v_mov_b64_e32 v[76:77], v[204:205]
	v_mov_b64_e32 v[78:79], v[206:207]
	v_lshlrev_b32_e32 v82, 16, v70
	v_add_f32_e32 v56, v56, v72
	v_add_f32_e32 v57, v57, v73
	v_add_f32_e32 v58, v58, v74
	v_mul_f32_e32 v56, 0xbfb8aa3b, v56
	v_mul_f32_e32 v57, 0xbfb8aa3b, v57
	v_mul_f32_e32 v58, 0xbfb8aa3b, v58
	v_exp_f32_e32 v56, v56
	v_exp_f32_e32 v57, v57
	v_exp_f32_e32 v58, v58
	v_and_b32_e32 v70, 0xffff0000, v70
	v_add_f32_e32 v56, 1.0, v56
	v_add_f32_e32 v57, 1.0, v57
	v_add_f32_e32 v58, 1.0, v58
	v_rcp_f32_e32 v56, v56
	v_rcp_f32_e32 v57, v57
	v_rcp_f32_e32 v58, v58
	v_lshlrev_b32_e32 v83, 16, v71
	v_add_f32_e32 v60, v60, v76
	v_mul_f32_e32 v72, v56, v82
	v_add_f32_e32 v56, v61, v77
	v_mul_f32_e32 v61, v57, v70
	v_add_f32_e32 v57, v62, v78
	v_mul_f32_e32 v62, v58, v83
	v_add_f32_e32 v58, v63, v79
	v_mul_f32_e32 v60, 0xbfb8aa3b, v60
	v_mul_f32_e32 v56, 0xbfb8aa3b, v56
	v_mul_f32_e32 v57, 0xbfb8aa3b, v57
	v_mul_f32_e32 v58, 0xbfb8aa3b, v58
	v_exp_f32_e32 v60, v60
	v_exp_f32_e32 v56, v56
	v_exp_f32_e32 v57, v57
	v_exp_f32_e32 v58, v58
	v_add_f32_e32 v59, v59, v75
	v_mul_f32_e32 v59, 0xbfb8aa3b, v59
	v_exp_f32_e32 v59, v59
	v_add_f32_e32 v60, 1.0, v60
	v_add_f32_e32 v56, 1.0, v56
	v_add_f32_e32 v57, 1.0, v57
	v_add_f32_e32 v58, 1.0, v58
	v_rcp_f32_e32 v60, v60
	v_rcp_f32_e32 v56, v56
	v_rcp_f32_e32 v57, v57
	v_rcp_f32_e32 v58, v58
	v_add_f32_e32 v59, 1.0, v59
	v_lshlrev_b32_e32 v80, 16, v68
	v_and_b32_e32 v68, 0xffff0000, v68
	v_lshlrev_b32_e32 v81, 16, v69
	v_and_b32_e32 v69, 0xffff0000, v69
	v_rcp_f32_e32 v59, v59
	v_mul_f32_e32 v60, v60, v80
	v_mul_f32_e32 v56, v56, v68
	v_mul_f32_e32 v57, v57, v81
	v_mul_f32_e32 v58, v58, v69
	v_cvt_pk_bf16_f32 v56, v60, v56
	v_cvt_pk_bf16_f32 v57, v57, v58
	v_cvt_pk_bf16_f32 v58, v72, v61
	v_lshlrev_b64 v[60:61], 12, v[66:67]
	v_and_b32_e32 v71, 0xffff0000, v71
	v_lshl_add_u64 v[60:61], s[12:13], 0, v[60:61]
	v_mul_f32_e32 v59, v59, v71
	v_lshl_add_u64 v[60:61], v[60:61], 0, v[192:193]
	v_cvt_pk_bf16_f32 v59, v62, v59
	global_store_dwordx4 v[60:61], v[56:59], off
	s_nop 1
	s_waitcnt vmcnt(13)
	v_mov_b64_e32 v[56:57], v[156:157]
	v_mov_b64_e32 v[58:59], v[158:159]
	s_nop 0
	v_mov_b64_e32 v[62:63], v[208:209]
	v_mov_b64_e32 v[64:65], v[210:211]
	v_mov_b64_e32 v[66:67], v[240:241]
	v_mov_b64_e32 v[68:69], v[242:243]
	v_lshlrev_b32_e32 v72, 16, v58
	v_add_f32_e32 v48, v48, v62
	v_add_f32_e32 v49, v49, v63
	v_add_f32_e32 v50, v50, v64
	v_mul_f32_e32 v48, 0xbfb8aa3b, v48
	v_mul_f32_e32 v49, 0xbfb8aa3b, v49
	v_mul_f32_e32 v50, 0xbfb8aa3b, v50
	v_exp_f32_e32 v48, v48
	v_exp_f32_e32 v49, v49
	v_exp_f32_e32 v50, v50
	v_and_b32_e32 v58, 0xffff0000, v58
	v_add_f32_e32 v48, 1.0, v48
	v_add_f32_e32 v49, 1.0, v49
	v_add_f32_e32 v50, 1.0, v50
	v_rcp_f32_e32 v48, v48
	v_rcp_f32_e32 v49, v49
	v_rcp_f32_e32 v50, v50
	v_lshlrev_b32_e32 v73, 16, v59
	v_mul_f32_e32 v62, v48, v72
	v_add_f32_e32 v48, v53, v67
	v_mul_f32_e32 v53, v49, v58
	v_add_f32_e32 v49, v54, v68
	v_mul_f32_e32 v54, v50, v73
	v_add_f32_e32 v50, v55, v69
	v_add_f32_e32 v52, v52, v66
	v_mul_f32_e32 v48, 0xbfb8aa3b, v48
	v_mul_f32_e32 v49, 0xbfb8aa3b, v49
	v_add_f32_e32 v51, v51, v65
	v_mul_f32_e32 v50, 0xbfb8aa3b, v50
	v_mul_f32_e32 v52, 0xbfb8aa3b, v52
	v_exp_f32_e32 v48, v48
	v_exp_f32_e32 v49, v49
	v_exp_f32_e32 v50, v50
	v_mul_f32_e32 v51, 0xbfb8aa3b, v51
	v_exp_f32_e32 v52, v52
	v_exp_f32_e32 v51, v51
	v_add_f32_e32 v48, 1.0, v48
	v_add_f32_e32 v49, 1.0, v49
	v_add_f32_e32 v50, 1.0, v50
	v_add_f32_e32 v52, 1.0, v52
	v_rcp_f32_e32 v48, v48
	v_rcp_f32_e32 v49, v49
	v_rcp_f32_e32 v50, v50
	v_add_f32_e32 v51, 1.0, v51
	v_rcp_f32_e32 v52, v52
	v_rcp_f32_e32 v51, v51
	v_lshlrev_b32_e32 v70, 16, v56
	v_and_b32_e32 v56, 0xffff0000, v56
	v_lshlrev_b32_e32 v71, 16, v57
	v_and_b32_e32 v57, 0xffff0000, v57
	v_and_b32_e32 v59, 0xffff0000, v59
	v_mul_f32_e32 v48, v48, v56
	v_mul_f32_e32 v49, v49, v71
	v_mul_f32_e32 v50, v50, v57
	v_mul_f32_e32 v52, v52, v70
	v_mul_f32_e32 v51, v51, v59
	v_cvt_pk_bf16_f32 v48, v52, v48
	v_cvt_pk_bf16_f32 v49, v49, v50
	v_cvt_pk_bf16_f32 v50, v62, v53
	v_cvt_pk_bf16_f32 v51, v54, v51
	global_store_dwordx4 v[60:61], v[48:51], off offset:256
	s_nop 1
	v_add_u32_e32 v50, 0x90, v128
	v_ashrrev_i32_e32 v51, 31, v50
	v_lshlrev_b64 v[48:49], 10, v[50:51]
	v_lshl_add_u64 v[48:49], s[14:15], 0, v[48:49]
	v_lshl_add_u64 v[48:49], v[48:49], 0, v[192:193]
	s_nop 1
	s_waitcnt vmcnt(12)
	v_mov_b64_e32 v[52:53], v[160:161]
	v_mov_b64_e32 v[54:55], v[162:163]
	v_mov_b64_e32 v[56:57], v[200:201]
	v_mov_b64_e32 v[58:59], v[202:203]
	v_mov_b64_e32 v[60:61], v[204:205]
	v_mov_b64_e32 v[62:63], v[206:207]
	v_lshlrev_b32_e32 v66, 16, v54
	v_add_f32_e32 v40, v40, v56
	v_add_f32_e32 v41, v41, v57
	v_add_f32_e32 v42, v42, v58
	v_mul_f32_e32 v40, 0xbfb8aa3b, v40
	v_mul_f32_e32 v41, 0xbfb8aa3b, v41
	v_mul_f32_e32 v42, 0xbfb8aa3b, v42
	v_exp_f32_e32 v40, v40
	v_exp_f32_e32 v41, v41
	v_exp_f32_e32 v42, v42
	v_and_b32_e32 v54, 0xffff0000, v54
	v_add_f32_e32 v40, 1.0, v40
	v_add_f32_e32 v41, 1.0, v41
	v_add_f32_e32 v42, 1.0, v42
	v_rcp_f32_e32 v40, v40
	v_rcp_f32_e32 v41, v41
	v_rcp_f32_e32 v42, v42
	v_lshlrev_b32_e32 v67, 16, v55
	v_add_f32_e32 v44, v44, v60
	v_mul_f32_e32 v56, v40, v66
	v_add_f32_e32 v40, v45, v61
	v_mul_f32_e32 v45, v41, v54
	v_add_f32_e32 v41, v46, v62
	v_mul_f32_e32 v46, v42, v67
	v_add_f32_e32 v42, v47, v63
	v_mul_f32_e32 v44, 0xbfb8aa3b, v44
	v_mul_f32_e32 v40, 0xbfb8aa3b, v40
	v_mul_f32_e32 v41, 0xbfb8aa3b, v41
	v_mul_f32_e32 v42, 0xbfb8aa3b, v42
	v_exp_f32_e32 v44, v44
	v_exp_f32_e32 v40, v40
	v_exp_f32_e32 v41, v41
	v_exp_f32_e32 v42, v42
	v_add_f32_e32 v43, v43, v59
	v_mul_f32_e32 v43, 0xbfb8aa3b, v43
	v_exp_f32_e32 v43, v43
	v_add_f32_e32 v44, 1.0, v44
	v_add_f32_e32 v40, 1.0, v40
	v_add_f32_e32 v41, 1.0, v41
	v_add_f32_e32 v42, 1.0, v42
	v_rcp_f32_e32 v44, v44
	v_rcp_f32_e32 v40, v40
	v_rcp_f32_e32 v41, v41
	v_rcp_f32_e32 v42, v42
	v_add_f32_e32 v43, 1.0, v43
	v_lshlrev_b32_e32 v64, 16, v52
	v_and_b32_e32 v52, 0xffff0000, v52
	v_lshlrev_b32_e32 v65, 16, v53
	v_and_b32_e32 v53, 0xffff0000, v53
	v_rcp_f32_e32 v43, v43
	v_mul_f32_e32 v44, v44, v64
	v_mul_f32_e32 v40, v40, v52
	v_mul_f32_e32 v41, v41, v65
	v_mul_f32_e32 v42, v42, v53
	v_cvt_pk_bf16_f32 v40, v44, v40
	v_cvt_pk_bf16_f32 v41, v41, v42
	v_cvt_pk_bf16_f32 v42, v56, v45
	v_lshlrev_b64 v[44:45], 12, v[50:51]
	v_and_b32_e32 v55, 0xffff0000, v55
	v_lshl_add_u64 v[44:45], s[12:13], 0, v[44:45]
	v_mul_f32_e32 v43, v43, v55
	v_lshl_add_u64 v[44:45], v[44:45], 0, v[192:193]
	v_cvt_pk_bf16_f32 v43, v46, v43
	global_store_dwordx4 v[44:45], v[40:43], off
	s_nop 1
	s_waitcnt vmcnt(11)
	v_mov_b64_e32 v[40:41], v[164:165]
	v_mov_b64_e32 v[42:43], v[166:167]
	s_nop 0
	v_mov_b64_e32 v[46:47], v[208:209]
	v_mov_b64_e32 v[48:49], v[210:211]
	v_mov_b64_e32 v[50:51], v[240:241]
	v_mov_b64_e32 v[52:53], v[242:243]
	v_lshlrev_b32_e32 v56, 16, v42
	v_add_f32_e32 v32, v32, v46
	v_add_f32_e32 v33, v33, v47
	v_add_f32_e32 v34, v34, v48
	v_mul_f32_e32 v32, 0xbfb8aa3b, v32
	v_mul_f32_e32 v33, 0xbfb8aa3b, v33
	v_mul_f32_e32 v34, 0xbfb8aa3b, v34
	v_exp_f32_e32 v32, v32
	v_exp_f32_e32 v33, v33
	v_exp_f32_e32 v34, v34
	v_and_b32_e32 v42, 0xffff0000, v42
	v_add_f32_e32 v32, 1.0, v32
	v_add_f32_e32 v33, 1.0, v33
	v_add_f32_e32 v34, 1.0, v34
	v_rcp_f32_e32 v32, v32
	v_rcp_f32_e32 v33, v33
	v_rcp_f32_e32 v34, v34
	v_lshlrev_b32_e32 v57, 16, v43
	v_mul_f32_e32 v46, v32, v56
	v_add_f32_e32 v32, v37, v51
	v_mul_f32_e32 v37, v33, v42
	v_add_f32_e32 v33, v38, v52
	v_mul_f32_e32 v38, v34, v57
	v_add_f32_e32 v34, v39, v53
	v_add_f32_e32 v36, v36, v50
	v_mul_f32_e32 v32, 0xbfb8aa3b, v32
	v_mul_f32_e32 v33, 0xbfb8aa3b, v33
	v_add_f32_e32 v35, v35, v49
	v_mul_f32_e32 v34, 0xbfb8aa3b, v34
	v_mul_f32_e32 v36, 0xbfb8aa3b, v36
	v_exp_f32_e32 v32, v32
	v_exp_f32_e32 v33, v33
	v_exp_f32_e32 v34, v34
	v_mul_f32_e32 v35, 0xbfb8aa3b, v35
	v_exp_f32_e32 v36, v36
	v_exp_f32_e32 v35, v35
	v_add_f32_e32 v32, 1.0, v32
	v_add_f32_e32 v33, 1.0, v33
	v_add_f32_e32 v34, 1.0, v34
	v_add_f32_e32 v36, 1.0, v36
	v_rcp_f32_e32 v32, v32
	v_rcp_f32_e32 v33, v33
	v_rcp_f32_e32 v34, v34
	v_add_f32_e32 v35, 1.0, v35
	v_rcp_f32_e32 v36, v36
	v_rcp_f32_e32 v35, v35
	v_lshlrev_b32_e32 v54, 16, v40
	v_and_b32_e32 v40, 0xffff0000, v40
	v_lshlrev_b32_e32 v55, 16, v41
	v_and_b32_e32 v41, 0xffff0000, v41
	v_and_b32_e32 v43, 0xffff0000, v43
	v_mul_f32_e32 v32, v32, v40
	v_mul_f32_e32 v33, v33, v55
	v_mul_f32_e32 v34, v34, v41
	v_mul_f32_e32 v36, v36, v54
	v_mul_f32_e32 v35, v35, v43
	v_cvt_pk_bf16_f32 v32, v36, v32
	v_cvt_pk_bf16_f32 v33, v33, v34
	v_cvt_pk_bf16_f32 v34, v46, v37
	v_cvt_pk_bf16_f32 v35, v38, v35
	global_store_dwordx4 v[44:45], v[32:35], off offset:256
	s_nop 1
	v_add_u32_e32 v34, 0xa0, v128
	v_ashrrev_i32_e32 v35, 31, v34
	v_lshlrev_b64 v[32:33], 10, v[34:35]
	v_lshl_add_u64 v[32:33], s[14:15], 0, v[32:33]
	v_lshl_add_u64 v[32:33], v[32:33], 0, v[192:193]
	s_nop 1
	s_waitcnt vmcnt(10)
	v_mov_b64_e32 v[36:37], v[168:169]
	v_mov_b64_e32 v[38:39], v[170:171]
	v_mov_b64_e32 v[40:41], v[200:201]
	v_mov_b64_e32 v[42:43], v[202:203]
	v_mov_b64_e32 v[44:45], v[204:205]
	v_mov_b64_e32 v[46:47], v[206:207]
	v_lshlrev_b32_e32 v50, 16, v38
	v_add_f32_e32 v24, v24, v40
	v_add_f32_e32 v25, v25, v41
	v_add_f32_e32 v26, v26, v42
	v_mul_f32_e32 v24, 0xbfb8aa3b, v24
	v_mul_f32_e32 v25, 0xbfb8aa3b, v25
	v_mul_f32_e32 v26, 0xbfb8aa3b, v26
	v_exp_f32_e32 v24, v24
	v_exp_f32_e32 v25, v25
	v_exp_f32_e32 v26, v26
	v_and_b32_e32 v38, 0xffff0000, v38
	v_add_f32_e32 v24, 1.0, v24
	v_add_f32_e32 v25, 1.0, v25
	v_add_f32_e32 v26, 1.0, v26
	v_rcp_f32_e32 v24, v24
	v_rcp_f32_e32 v25, v25
	v_rcp_f32_e32 v26, v26
	v_lshlrev_b32_e32 v51, 16, v39
	v_add_f32_e32 v28, v28, v44
	v_mul_f32_e32 v40, v24, v50
	v_add_f32_e32 v24, v29, v45
	v_mul_f32_e32 v29, v25, v38
	v_add_f32_e32 v25, v30, v46
	v_mul_f32_e32 v30, v26, v51
	v_add_f32_e32 v26, v31, v47
	v_mul_f32_e32 v28, 0xbfb8aa3b, v28
	v_mul_f32_e32 v24, 0xbfb8aa3b, v24
	v_mul_f32_e32 v25, 0xbfb8aa3b, v25
	v_mul_f32_e32 v26, 0xbfb8aa3b, v26
	v_exp_f32_e32 v28, v28
	v_exp_f32_e32 v24, v24
	v_exp_f32_e32 v25, v25
	v_exp_f32_e32 v26, v26
	v_add_f32_e32 v27, v27, v43
	v_mul_f32_e32 v27, 0xbfb8aa3b, v27
	v_exp_f32_e32 v27, v27
	v_add_f32_e32 v28, 1.0, v28
	v_add_f32_e32 v24, 1.0, v24
	v_add_f32_e32 v25, 1.0, v25
	v_add_f32_e32 v26, 1.0, v26
	v_rcp_f32_e32 v28, v28
	v_rcp_f32_e32 v24, v24
	v_rcp_f32_e32 v25, v25
	v_rcp_f32_e32 v26, v26
	v_add_f32_e32 v27, 1.0, v27
	v_lshlrev_b32_e32 v48, 16, v36
	v_and_b32_e32 v36, 0xffff0000, v36
	v_lshlrev_b32_e32 v49, 16, v37
	v_and_b32_e32 v37, 0xffff0000, v37
	v_rcp_f32_e32 v27, v27
	v_mul_f32_e32 v28, v28, v48
	v_mul_f32_e32 v24, v24, v36
	v_mul_f32_e32 v25, v25, v49
	v_mul_f32_e32 v26, v26, v37
	v_cvt_pk_bf16_f32 v24, v28, v24
	v_cvt_pk_bf16_f32 v25, v25, v26
	v_cvt_pk_bf16_f32 v26, v40, v29
	v_lshlrev_b64 v[28:29], 12, v[34:35]
	v_and_b32_e32 v39, 0xffff0000, v39
	v_lshl_add_u64 v[28:29], s[12:13], 0, v[28:29]
	v_mul_f32_e32 v27, v27, v39
	v_lshl_add_u64 v[28:29], v[28:29], 0, v[192:193]
	v_cvt_pk_bf16_f32 v27, v30, v27
	global_store_dwordx4 v[28:29], v[24:27], off
	s_nop 1
	s_waitcnt vmcnt(9)
	v_mov_b64_e32 v[24:25], v[172:173]
	v_mov_b64_e32 v[26:27], v[174:175]
	s_nop 0
	v_mov_b64_e32 v[30:31], v[208:209]
	v_mov_b64_e32 v[32:33], v[210:211]
	v_mov_b64_e32 v[34:35], v[240:241]
	v_mov_b64_e32 v[36:37], v[242:243]
	v_lshlrev_b32_e32 v40, 16, v26
	v_add_f32_e32 v16, v16, v30
	v_add_f32_e32 v17, v17, v31
	v_add_f32_e32 v18, v18, v32
	v_mul_f32_e32 v16, 0xbfb8aa3b, v16
	v_mul_f32_e32 v17, 0xbfb8aa3b, v17
	v_mul_f32_e32 v18, 0xbfb8aa3b, v18
	v_exp_f32_e32 v16, v16
	v_exp_f32_e32 v17, v17
	v_exp_f32_e32 v18, v18
	v_and_b32_e32 v26, 0xffff0000, v26
	v_add_f32_e32 v16, 1.0, v16
	v_add_f32_e32 v17, 1.0, v17
	v_add_f32_e32 v18, 1.0, v18
	v_rcp_f32_e32 v16, v16
	v_rcp_f32_e32 v17, v17
	v_rcp_f32_e32 v18, v18
	v_lshlrev_b32_e32 v41, 16, v27
	v_mul_f32_e32 v30, v16, v40
	v_add_f32_e32 v16, v21, v35
	v_mul_f32_e32 v21, v17, v26
	v_add_f32_e32 v17, v22, v36
	v_mul_f32_e32 v22, v18, v41
	v_add_f32_e32 v18, v23, v37
	v_add_f32_e32 v20, v20, v34
	v_mul_f32_e32 v16, 0xbfb8aa3b, v16
	v_mul_f32_e32 v17, 0xbfb8aa3b, v17
	v_add_f32_e32 v19, v19, v33
	v_mul_f32_e32 v18, 0xbfb8aa3b, v18
	v_mul_f32_e32 v20, 0xbfb8aa3b, v20
	v_exp_f32_e32 v16, v16
	v_exp_f32_e32 v17, v17
	v_exp_f32_e32 v18, v18
	v_mul_f32_e32 v19, 0xbfb8aa3b, v19
	v_exp_f32_e32 v20, v20
	v_exp_f32_e32 v19, v19
	v_add_f32_e32 v16, 1.0, v16
	v_add_f32_e32 v17, 1.0, v17
	v_add_f32_e32 v18, 1.0, v18
	v_add_f32_e32 v20, 1.0, v20
	v_rcp_f32_e32 v16, v16
	v_rcp_f32_e32 v17, v17
	v_rcp_f32_e32 v18, v18
	v_add_f32_e32 v19, 1.0, v19
	v_rcp_f32_e32 v20, v20
	v_rcp_f32_e32 v19, v19
	v_lshlrev_b32_e32 v38, 16, v24
	v_and_b32_e32 v24, 0xffff0000, v24
	v_lshlrev_b32_e32 v39, 16, v25
	v_and_b32_e32 v25, 0xffff0000, v25
	v_and_b32_e32 v27, 0xffff0000, v27
	v_mul_f32_e32 v16, v16, v24
	v_mul_f32_e32 v17, v17, v39
	v_mul_f32_e32 v18, v18, v25
	v_mul_f32_e32 v20, v20, v38
	v_mul_f32_e32 v19, v19, v27
	v_cvt_pk_bf16_f32 v16, v20, v16
	v_cvt_pk_bf16_f32 v17, v17, v18
	v_cvt_pk_bf16_f32 v18, v30, v21
	v_cvt_pk_bf16_f32 v19, v22, v19
	global_store_dwordx4 v[28:29], v[16:19], off offset:256
	s_nop 1
	v_add_u32_e32 v18, 0xb0, v128
	v_ashrrev_i32_e32 v19, 31, v18
	v_lshlrev_b64 v[16:17], 10, v[18:19]
	v_lshl_add_u64 v[16:17], s[14:15], 0, v[16:17]
	v_lshl_add_u64 v[16:17], v[16:17], 0, v[192:193]
	s_nop 1
	s_waitcnt vmcnt(8)
	v_mov_b64_e32 v[20:21], v[176:177]
	v_mov_b64_e32 v[22:23], v[178:179]
	v_mov_b64_e32 v[24:25], v[200:201]
	v_mov_b64_e32 v[26:27], v[202:203]
	v_mov_b64_e32 v[28:29], v[204:205]
	v_mov_b64_e32 v[30:31], v[206:207]
	v_lshlrev_b32_e32 v34, 16, v22
	v_add_f32_e32 v8, v8, v24
	v_add_f32_e32 v9, v9, v25
	v_add_f32_e32 v10, v10, v26
	v_mul_f32_e32 v8, 0xbfb8aa3b, v8
	v_mul_f32_e32 v9, 0xbfb8aa3b, v9
	v_mul_f32_e32 v10, 0xbfb8aa3b, v10
	v_exp_f32_e32 v8, v8
	v_exp_f32_e32 v9, v9
	v_exp_f32_e32 v10, v10
	v_and_b32_e32 v22, 0xffff0000, v22
	v_add_f32_e32 v8, 1.0, v8
	v_add_f32_e32 v9, 1.0, v9
	v_add_f32_e32 v10, 1.0, v10
	v_rcp_f32_e32 v8, v8
	v_rcp_f32_e32 v9, v9
	v_rcp_f32_e32 v10, v10
	v_lshlrev_b32_e32 v35, 16, v23
	v_add_f32_e32 v12, v12, v28
	v_mul_f32_e32 v24, v8, v34
	v_add_f32_e32 v8, v13, v29
	v_mul_f32_e32 v13, v9, v22
	v_add_f32_e32 v9, v14, v30
	v_mul_f32_e32 v14, v10, v35
	v_add_f32_e32 v10, v15, v31
	v_mul_f32_e32 v12, 0xbfb8aa3b, v12
	v_mul_f32_e32 v8, 0xbfb8aa3b, v8
	v_mul_f32_e32 v9, 0xbfb8aa3b, v9
	v_mul_f32_e32 v10, 0xbfb8aa3b, v10
	v_exp_f32_e32 v12, v12
	v_exp_f32_e32 v8, v8
	v_exp_f32_e32 v9, v9
	v_exp_f32_e32 v10, v10
	v_add_f32_e32 v11, v11, v27
	v_mul_f32_e32 v11, 0xbfb8aa3b, v11
	v_exp_f32_e32 v11, v11
	v_add_f32_e32 v12, 1.0, v12
	v_add_f32_e32 v8, 1.0, v8
	v_add_f32_e32 v9, 1.0, v9
	v_add_f32_e32 v10, 1.0, v10
	v_rcp_f32_e32 v12, v12
	v_rcp_f32_e32 v8, v8
	v_rcp_f32_e32 v9, v9
	v_rcp_f32_e32 v10, v10
	v_add_f32_e32 v11, 1.0, v11
	v_lshlrev_b32_e32 v32, 16, v20
	v_and_b32_e32 v20, 0xffff0000, v20
	v_lshlrev_b32_e32 v33, 16, v21
	v_and_b32_e32 v21, 0xffff0000, v21
	v_rcp_f32_e32 v11, v11
	v_mul_f32_e32 v12, v12, v32
	v_mul_f32_e32 v8, v8, v20
	v_mul_f32_e32 v9, v9, v33
	v_mul_f32_e32 v10, v10, v21
	v_cvt_pk_bf16_f32 v8, v12, v8
	v_cvt_pk_bf16_f32 v9, v9, v10
	v_cvt_pk_bf16_f32 v10, v24, v13
	v_lshlrev_b64 v[12:13], 12, v[18:19]
	v_and_b32_e32 v23, 0xffff0000, v23
	v_lshl_add_u64 v[12:13], s[12:13], 0, v[12:13]
	v_mul_f32_e32 v11, v11, v23
	v_lshl_add_u64 v[12:13], v[12:13], 0, v[192:193]
	v_cvt_pk_bf16_f32 v11, v14, v11
	global_store_dwordx4 v[12:13], v[8:11], off
	s_nop 1
	s_waitcnt vmcnt(7)
	v_mov_b64_e32 v[8:9], v[180:181]
	v_mov_b64_e32 v[10:11], v[182:183]
	s_nop 0
	v_mov_b64_e32 v[14:15], v[208:209]
	v_mov_b64_e32 v[16:17], v[210:211]
	v_mov_b64_e32 v[18:19], v[240:241]
	v_mov_b64_e32 v[20:21], v[242:243]
	s_mov_b64 s[10:11], 0
	v_lshlrev_b32_e32 v24, 16, v10
	v_add_f32_e32 v0, v0, v14
	v_add_f32_e32 v1, v1, v15
	v_add_f32_e32 v2, v2, v16
	v_mul_f32_e32 v0, 0xbfb8aa3b, v0
	v_mul_f32_e32 v1, 0xbfb8aa3b, v1
	v_mul_f32_e32 v2, 0xbfb8aa3b, v2
	v_exp_f32_e32 v0, v0
	v_exp_f32_e32 v1, v1
	v_exp_f32_e32 v2, v2
	v_and_b32_e32 v10, 0xffff0000, v10
	v_add_f32_e32 v0, 1.0, v0
	v_add_f32_e32 v1, 1.0, v1
	v_add_f32_e32 v2, 1.0, v2
	v_rcp_f32_e32 v0, v0
	v_rcp_f32_e32 v1, v1
	v_rcp_f32_e32 v2, v2
	v_lshlrev_b32_e32 v25, 16, v11
	v_mul_f32_e32 v14, v0, v24
	v_add_f32_e32 v0, v5, v19
	v_mul_f32_e32 v5, v1, v10
	v_add_f32_e32 v1, v6, v20
	v_mul_f32_e32 v6, v2, v25
	v_add_f32_e32 v2, v7, v21
	v_add_f32_e32 v3, v3, v17
	v_add_f32_e32 v4, v4, v18
	v_mul_f32_e32 v0, 0xbfb8aa3b, v0
	v_mul_f32_e32 v1, 0xbfb8aa3b, v1
	v_mul_f32_e32 v2, 0xbfb8aa3b, v2
	v_mul_f32_e32 v3, 0xbfb8aa3b, v3
	v_mul_f32_e32 v4, 0xbfb8aa3b, v4
	v_exp_f32_e32 v0, v0
	v_exp_f32_e32 v1, v1
	v_exp_f32_e32 v2, v2
	v_exp_f32_e32 v3, v3
	v_exp_f32_e32 v4, v4
	v_add_f32_e32 v0, 1.0, v0
	v_add_f32_e32 v1, 1.0, v1
	v_add_f32_e32 v2, 1.0, v2
	v_add_f32_e32 v3, 1.0, v3
	v_add_f32_e32 v4, 1.0, v4
	v_rcp_f32_e32 v0, v0
	v_rcp_f32_e32 v1, v1
	v_rcp_f32_e32 v2, v2
	v_rcp_f32_e32 v3, v3
	v_rcp_f32_e32 v4, v4
	v_lshlrev_b32_e32 v22, 16, v8
	v_and_b32_e32 v8, 0xffff0000, v8
	v_lshlrev_b32_e32 v23, 16, v9
	v_and_b32_e32 v9, 0xffff0000, v9
	v_and_b32_e32 v11, 0xffff0000, v11
	v_mul_f32_e32 v0, v0, v8
	v_mul_f32_e32 v1, v1, v23
	v_mul_f32_e32 v2, v2, v9
	v_mul_f32_e32 v3, v3, v11
	v_mul_f32_e32 v4, v4, v22
	v_cvt_pk_bf16_f32 v0, v4, v0
	v_cvt_pk_bf16_f32 v1, v1, v2
	v_cvt_pk_bf16_f32 v2, v14, v5
	v_cvt_pk_bf16_f32 v3, v6, v3
	global_store_dwordx4 v[12:13], v[0:3], off offset:256
	s_waitcnt vmcnt(0)
	s_barrier
	s_barrier

.LBB0_524:
	s_or_b64 exec, exec, s[20:21]
	s_mul_hi_i32 s11, s25, 0x55555555
	s_sub_i32 s11, s11, s25
	s_lshr_b32 s18, s11, 31
	s_ashr_i32 s20, s11, 1
	s_add_i32 s20, s20, s18
	s_add_i32 s24, s20, 15
	s_waitcnt lgkmcnt(0)
	s_add_u32 s18, s14, 0x16200000
	s_addc_u32 s19, s15, 0
	s_ashr_i32 s28, s4, 6
	s_and_b32 s23, s28, 3
	s_lshl_b32 s11, s24, 7
	s_lshl_b32 s21, s23, 5
	s_or_b32 s26, s21, s11
	s_ashr_i32 s11, s10, 31
	s_mulk_i32 s28, 0x2200
	s_lshl_b64 s[14:15], s[10:11], 11
	s_add_i32 s11, s28, 0
	s_add_i32 s11, s11, 0x13000
	v_and_b32_e32 v1, 31, v0
	v_bfe_u32 v239, v0, 5, 1
	v_mov_b32_e32 v3, s11
	v_or_b32_e32 v2, s26, v1
	v_mad_u32_u24 v3, v1, s95, v3
	v_lshlrev_b32_e32 v192, 4, v239
	v_add_u32_e32 v240, v3, v192
	v_ashrrev_i32_e32 v3, 31, v2
	v_lshl_add_u64 v[200:201], s[14:15], 0, v[2:3]
	v_mov_b64_e32 v[2:3], s[18:19]
	v_mad_u64_u32 v[2:3], s[14:15], v200, s55, v[2:3]
	s_lshl_b32 s14, s27, 7
	v_mad_i32_i24 v3, v201, s55, v3
	s_ashr_i32 s15, s14, 31
	v_lshl_add_u64 v[2:3], s[14:15], 1, v[2:3]
	v_lshl_add_u64 v[2:3], v[2:3], 0, v[192:193]
	s_mov_b64 s[28:29], 0x1600
	v_lshl_add_u64 v[6:7], v[2:3], 0, s[28:29]
	v_add_co_u32_e32 v2, vcc, s3, v2
	v_and_b32_e32 v8, 63, v0
	s_nop 0
	v_addc_co_u32_e32 v3, vcc, 0, v3, vcc
	global_load_dwordx4 v[2:5], v[2:3], off offset:1536
	global_load_dwordx4 v[12:15], v[6:7], off offset:32
	global_load_dwordx4 v[16:19], v[6:7], off offset:64
	global_load_dwordx4 v[20:23], v[6:7], off offset:96
	global_load_dwordx4 v[24:27], v[6:7], off offset:128
	global_load_dwordx4 v[28:31], v[6:7], off offset:160
	global_load_dwordx4 v[32:35], v[6:7], off offset:192
	global_load_dwordx4 v[36:39], v[6:7], off offset:224
	s_ashr_i32 s22, s4, 8
	s_cmp_gt_i32 s25, 47
	v_lshlrev_b32_e32 v241, 2, v8
	s_waitcnt vmcnt(7)
	ds_write_b128 v240, v[2:5]
	s_waitcnt vmcnt(6)
	ds_write_b128 v240, v[12:15] offset:32
	s_waitcnt vmcnt(5)
	ds_write_b128 v240, v[16:19] offset:64
	s_waitcnt vmcnt(4)
	ds_write_b128 v240, v[20:23] offset:96
	s_waitcnt vmcnt(3)
	ds_write_b128 v240, v[24:27] offset:128
	s_waitcnt vmcnt(2)
	ds_write_b128 v240, v[28:31] offset:160
	s_waitcnt vmcnt(1)
	ds_write_b128 v240, v[32:35] offset:192
	s_waitcnt vmcnt(0)
	ds_write_b128 v240, v[36:39] offset:224
	s_cbranch_scc1 .LBB0_603
	s_mul_hi_i32 s11, s10, 0x1400000
	s_mul_i32 s10, s10, 0x1400000
	s_add_u32 s18, s18, s10
	s_addc_u32 s19, s19, s11
	s_lshl_b64 s[10:11], s[14:15], 1
	v_add_u32_e32 v2, 0x200, v0
	s_add_u32 s10, s18, s10
	v_ashrrev_i32_e32 v7, 4, v2
	v_lshlrev_b32_e32 v2, 4, v0
	s_addc_u32 s11, s19, s11
	v_and_b32_e32 v202, 0xf0, v2
	v_mov_b32_e32 v203, v193
	v_lshl_add_u64 v[2:3], s[10:11], 0, v[202:203]
	s_mov_b64 s[10:11], 0x1c00
	v_lshl_add_u64 v[204:205], v[2:3], 0, s[10:11]
	s_mov_b64 s[10:11], 0x2200
	v_lshl_add_u64 v[206:207], v[2:3], 0, s[10:11]
	v_ashrrev_i32_e32 v6, 4, v0
	v_mad_i64_i32 v[2:3], s[10:11], v7, s55, v[206:207]
	v_mad_i64_i32 v[4:5], s[10:11], v6, s55, v[206:207]
	global_load_dwordx4 v[188:191], v[2:3], off
	global_load_dwordx4 v[184:187], v[4:5], off
	v_mad_i64_i32 v[2:3], s[10:11], v7, s55, v[204:205]
	v_mad_i64_i32 v[4:5], s[10:11], v6, s55, v[204:205]
	global_load_dwordx4 v[180:183], v[2:3], off
	global_load_dwordx4 v[176:179], v[4:5], off
	v_bfe_u32 v3, v0, 2, 2
	v_and_b32_e32 v4, 16, v0
	v_lshrrev_b32_e32 v0, 3, v0
	s_lshl_b32 s25, s22, 5
	v_and_b32_e32 v0, 4, v0
	v_or_b32_e32 v2, s25, v1
	v_or3_b32 v0, v0, v3, s25
	v_mad_i64_i32 v[210:211], s[10:11], v6, s55, 0
	v_mad_i64_i32 v[212:213], s[10:11], v7, s55, 0
	v_mul_lo_u32 v246, v2, s95
	v_lshlrev_b32_e32 v2, 2, v239
	v_mul_lo_u32 v247, v0, s96
	v_and_or_b32 v0, v241, 12, v4
	v_lshlrev_b32_e32 v248, 1, v0
	s_lshl_b32 s10, s20, 7
	v_sub_u32_e32 v0, v1, v2
	v_mov_b32_e32 v14, v193
	v_mov_b32_e32 v15, v193
	s_lshl_b32 s24, s24, 1
	v_mul_lo_u32 v242, v6, s95
	v_mul_lo_u32 v243, v7, s95
	v_mul_lo_u32 v244, v6, s96
	v_mul_lo_u32 v245, v7, s96
	s_or_b32 s10, s10, s21
	v_subrev_u32_e32 v249, s25, v0
	v_mov_b32_e32 v0, v193
	v_mov_b32_e32 v1, v193
	v_mov_b32_e32 v2, v193
	v_mov_b32_e32 v3, v193
	v_mov_b32_e32 v4, v193
	v_mov_b32_e32 v5, v193
	v_mov_b32_e32 v6, v193
	v_mov_b32_e32 v7, v193
	v_mov_b32_e32 v8, v193
	v_mov_b32_e32 v9, v193
	v_mov_b32_e32 v10, v193
	v_mov_b32_e32 v11, v193
	v_mov_b32_e32 v12, v193
	v_mov_b32_e32 v13, v193
	v_mov_b32_e32 v208, 0
	v_mov_b64_e32 v[46:47], v[14:15]
	v_mov_b64_e32 v[78:79], v[14:15]
	v_mov_b64_e32 v[126:127], v[14:15]
	v_mov_b64_e32 v[30:31], v[14:15]
	v_mov_b64_e32 v[62:63], v[14:15]
	v_mov_b64_e32 v[94:95], v[14:15]
	v_mov_b64_e32 v[110:111], v[14:15]
	s_add_i32 s24, s24, 2
	s_or_b32 s26, s26, 31
	s_add_i32 s27, s10, 0x741
	s_mov_b32 s28, 0
	v_mov_b32_e32 v250, 0xf149f2ca
	v_mov_b64_e32 v[44:45], v[12:13]
	v_mov_b64_e32 v[42:43], v[10:11]
	v_mov_b64_e32 v[40:41], v[8:9]
	v_mov_b64_e32 v[38:39], v[6:7]
	v_mov_b64_e32 v[36:37], v[4:5]
	v_mov_b64_e32 v[34:35], v[2:3]
	v_mov_b64_e32 v[32:33], v[0:1]
	v_mov_b64_e32 v[76:77], v[12:13]
	v_mov_b64_e32 v[74:75], v[10:11]
	v_mov_b64_e32 v[72:73], v[8:9]
	v_mov_b64_e32 v[70:71], v[6:7]
	v_mov_b64_e32 v[68:69], v[4:5]
	v_mov_b64_e32 v[66:67], v[2:3]
	v_mov_b64_e32 v[64:65], v[0:1]
	v_mov_b64_e32 v[124:125], v[12:13]
	v_mov_b64_e32 v[122:123], v[10:11]
	v_mov_b64_e32 v[120:121], v[8:9]
	v_mov_b64_e32 v[118:119], v[6:7]
	v_mov_b64_e32 v[116:117], v[4:5]
	v_mov_b64_e32 v[114:115], v[2:3]
	v_mov_b64_e32 v[112:113], v[0:1]
	v_mov_b64_e32 v[28:29], v[12:13]
	v_mov_b64_e32 v[26:27], v[10:11]
	v_mov_b64_e32 v[24:25], v[8:9]
	v_mov_b64_e32 v[22:23], v[6:7]
	v_mov_b64_e32 v[20:21], v[4:5]
	v_mov_b64_e32 v[18:19], v[2:3]
	v_mov_b64_e32 v[16:17], v[0:1]
	v_mov_b64_e32 v[60:61], v[12:13]
	v_mov_b64_e32 v[58:59], v[10:11]
	v_mov_b64_e32 v[56:57], v[8:9]
	v_mov_b64_e32 v[54:55], v[6:7]
	v_mov_b64_e32 v[52:53], v[4:5]
	v_mov_b64_e32 v[50:51], v[2:3]
	v_mov_b64_e32 v[48:49], v[0:1]
	v_mov_b64_e32 v[92:93], v[12:13]
	v_mov_b64_e32 v[90:91], v[10:11]
	v_mov_b64_e32 v[88:89], v[8:9]
	v_mov_b64_e32 v[86:87], v[6:7]
	v_mov_b64_e32 v[84:85], v[4:5]
	v_mov_b64_e32 v[82:83], v[2:3]
	v_mov_b64_e32 v[80:81], v[0:1]
	v_mov_b64_e32 v[108:109], v[12:13]
	v_mov_b64_e32 v[106:107], v[10:11]
	v_mov_b64_e32 v[104:105], v[8:9]
	v_mov_b64_e32 v[102:103], v[6:7]
	v_mov_b64_e32 v[100:101], v[4:5]
	v_mov_b64_e32 v[98:99], v[2:3]
	v_mov_b64_e32 v[96:97], v[0:1]
	s_mov_b32 s29, 0
	v_mov_b32_e32 v203, 0xf149f2ca
	v_mov_b32_e32 v209, v208
	s_branch .LBB0_528

.LBB0_611:
	s_andn2_b64 vcc, exec, s[18:19]
	s_waitcnt lgkmcnt(0)
	s_barrier
	s_cbranch_vccnz .LBB0_613
	v_div_scale_f32 v129, s[10:11], v133, v133, 1.0
	v_rcp_f32_e32 v131, v129
	s_add_u32 s16, s16, s74
	s_addc_u32 s17, s17, s75
	s_mov_b32 s4, 0xf800000
	v_fma_f32 v134, -v129, v131, 1.0
	v_fmac_f32_e32 v131, v134, v131
	v_div_scale_f32 v134, vcc, 1.0, v133, 1.0
	v_mul_f32_e32 v135, v134, v131
	v_fma_f32 v136, -v129, v135, v134
	v_fmac_f32_e32 v135, v136, v131
	v_fma_f32 v129, -v129, v135, v134
	v_div_fmas_f32 v129, v129, v131, v135
	v_div_fixup_f32 v134, v129, v133, 1.0
	v_div_scale_f32 v129, s[10:11], v132, v132, v236
	v_rcp_f32_e32 v131, v129
	s_mov_b64 s[10:11], 0x1fa00a00
	v_fma_f32 v133, -v129, v131, 1.0
	v_fmac_f32_e32 v131, v133, v131
	v_div_scale_f32 v133, vcc, v236, v132, v236
	v_mul_f32_e32 v135, v133, v131
	v_fma_f32 v136, -v129, v135, v133
	v_fmac_f32_e32 v135, v136, v131
	ds_read2st64_b32 v[208:209], v148 offset1:1
	ds_read2st64_b32 v[210:211], v148 offset0:2 offset1:3
	ds_read2st64_b32 v[204:205], v148 offset0:4 offset1:5
	ds_read2st64_b32 v[206:207], v148 offset0:6 offset1:7
	s_waitcnt vmcnt(0)
	ds_read2st64_b32 v[190:191], v148 offset0:8 offset1:9
	ds_read2st64_b32 v[202:203], v148 offset0:10 offset1:11
	ds_read2st64_b32 v[186:187], v148 offset0:12 offset1:13
	ds_read2st64_b32 v[188:189], v148 offset0:14 offset1:15
	ds_read2st64_b32 v[182:183], v148 offset0:16 offset1:17
	ds_read2st64_b32 v[184:185], v148 offset0:18 offset1:19
	ds_read2st64_b32 v[178:179], v148 offset0:20 offset1:21
	ds_read2st64_b32 v[180:181], v148 offset0:22 offset1:23
	ds_read2st64_b32 v[174:175], v148 offset0:24 offset1:25
	ds_read2st64_b32 v[176:177], v148 offset0:26 offset1:27
	ds_read2st64_b32 v[170:171], v148 offset0:28 offset1:29
	ds_read2st64_b32 v[172:173], v148 offset0:30 offset1:31
	ds_read2st64_b32 v[164:165], v148 offset0:32 offset1:33
	ds_read2st64_b32 v[166:167], v148 offset0:34 offset1:35
	ds_read2st64_b32 v[160:161], v148 offset0:36 offset1:37
	ds_read2st64_b32 v[162:163], v148 offset0:38 offset1:39
	ds_read2st64_b32 v[156:157], v148 offset0:40 offset1:41
	ds_read2st64_b32 v[158:159], v148 offset0:42 offset1:43
	ds_read2st64_b32 v[152:153], v148 offset0:44 offset1:45
	ds_read2st64_b32 v[154:155], v148 offset0:46 offset1:47
	ds_read2st64_b32 v[146:147], v148 offset0:48 offset1:49
	ds_read2st64_b32 v[150:151], v148 offset0:50 offset1:51
	ds_read2st64_b32 v[140:141], v148 offset0:52 offset1:53
	ds_read2st64_b32 v[142:143], v148 offset0:54 offset1:55
	ds_read2st64_b32 v[138:139], v148 offset0:56 offset1:57
	ds_read2st64_b32 v[136:137], v148 offset0:58 offset1:59
	v_fma_f32 v129, -v129, v135, v133
	v_div_fmas_f32 v129, v129, v131, v135
	v_div_fixup_f32 v132, v129, v132, v236
	s_waitcnt lgkmcnt(0)
	v_pk_mul_f32 v[136:137], v[130:131], v[136:137] op_sel_hi:[0,1]
	v_pk_fma_f32 v[26:27], v[26:27], v[128:129], v[136:137] op_sel_hi:[1,0,1]
	s_nop 0
	v_pk_mul_f32 v[26:27], v[132:133], v[26:27] op_sel_hi:[0,1]
	v_pk_fma_f32 v[26:27], v[10:11], v[134:135], v[26:27] op_sel_hi:[1,0,1] neg_lo:[0,0,1] neg_hi:[0,0,1]
	ds_read2st64_b32 v[10:11], v148 offset0:60 offset1:61
	v_pk_mul_f32 v[136:137], v[26:27], v[26:27]
	s_waitcnt lgkmcnt(0)
	v_pk_mul_f32 v[10:11], v[130:131], v[10:11] op_sel_hi:[0,1]
	v_pk_fma_f32 v[10:11], v[28:29], v[128:129], v[10:11] op_sel_hi:[1,0,1]
	s_nop 0
	v_pk_mul_f32 v[10:11], v[132:133], v[10:11] op_sel_hi:[0,1]
	v_pk_fma_f32 v[28:29], v[12:13], v[134:135], v[10:11] op_sel_hi:[1,0,1] neg_lo:[0,0,1] neg_hi:[0,0,1]
	ds_read2st64_b32 v[10:11], v148 offset0:62 offset1:63
	v_lshlrev_b32_e32 v12, 3, v239
	v_mov_b32_e32 v13, v193
	v_pk_mul_f32 v[144:145], v[28:29], v[28:29]
	s_waitcnt lgkmcnt(0)
	v_pk_mul_f32 v[10:11], v[130:131], v[10:11] op_sel_hi:[0,1]
	v_pk_fma_f32 v[10:11], v[30:31], v[128:129], v[10:11] op_sel_hi:[1,0,1]
	s_nop 0
	v_pk_mul_f32 v[10:11], v[132:133], v[10:11] op_sel_hi:[0,1]
	v_pk_fma_f32 v[30:31], v[14:15], v[134:135], v[10:11] op_sel_hi:[1,0,1] neg_lo:[0,0,1] neg_hi:[0,0,1]
	v_lshlrev_b64 v[10:11], 12, v[200:201]
	v_pk_mul_f32 v[200:201], v[130:131], v[210:211] op_sel_hi:[0,1]
	v_pk_fma_f32 v[98:99], v[98:99], v[128:129], v[200:201] op_sel_hi:[1,0,1]
	v_lshl_add_u64 v[10:11], s[12:13], 0, v[10:11]
	v_pk_mul_f32 v[98:99], v[132:133], v[98:99] op_sel_hi:[0,1]
	v_pk_fma_f32 v[98:99], v[114:115], v[134:135], v[98:99] op_sel_hi:[1,0,1] neg_lo:[0,0,1] neg_hi:[0,0,1]
	v_pk_mul_f32 v[114:115], v[130:131], v[208:209] op_sel_hi:[0,1]
	v_pk_fma_f32 v[96:97], v[96:97], v[128:129], v[114:115] op_sel_hi:[1,0,1]
	v_pk_mul_f32 v[200:201], v[98:99], v[98:99]
	v_pk_mul_f32 v[96:97], v[132:133], v[96:97] op_sel_hi:[0,1]
	v_pk_fma_f32 v[112:113], v[112:113], v[134:135], v[96:97] op_sel_hi:[1,0,1] neg_lo:[0,0,1] neg_hi:[0,0,1]
	v_pk_mul_f32 v[96:97], v[130:131], v[206:207] op_sel_hi:[0,1]
	v_pk_fma_f32 v[96:97], v[102:103], v[128:129], v[96:97] op_sel_hi:[1,0,1]
	v_pk_mul_f32 v[102:103], v[130:131], v[204:205] op_sel_hi:[0,1]
	v_pk_fma_f32 v[100:101], v[100:101], v[128:129], v[102:103] op_sel_hi:[1,0,1]
	v_pk_mul_f32 v[208:209], v[112:113], v[112:113]
	v_pk_mul_f32 v[100:101], v[132:133], v[100:101] op_sel_hi:[0,1]
	v_pk_fma_f32 v[114:115], v[116:117], v[134:135], v[100:101] op_sel_hi:[1,0,1] neg_lo:[0,0,1] neg_hi:[0,0,1]
	v_pk_mul_f32 v[100:101], v[130:131], v[202:203] op_sel_hi:[0,1]
	v_pk_fma_f32 v[100:101], v[106:107], v[128:129], v[100:101] op_sel_hi:[1,0,1]
	v_pk_mul_f32 v[106:107], v[130:131], v[186:187] op_sel_hi:[0,1]
	v_pk_fma_f32 v[106:107], v[108:109], v[128:129], v[106:107] op_sel_hi:[1,0,1]
	v_pk_mul_f32 v[96:97], v[132:133], v[96:97] op_sel_hi:[0,1]
	v_pk_mul_f32 v[106:107], v[132:133], v[106:107] op_sel_hi:[0,1]
	v_pk_fma_f32 v[108:109], v[124:125], v[134:135], v[106:107] op_sel_hi:[1,0,1] neg_lo:[0,0,1] neg_hi:[0,0,1]
	v_pk_mul_f32 v[106:107], v[130:131], v[184:185] op_sel_hi:[0,1]
	v_pk_fma_f32 v[82:83], v[82:83], v[128:129], v[106:107] op_sel_hi:[1,0,1]
	v_pk_mul_f32 v[116:117], v[114:115], v[114:115]
	v_pk_mul_f32 v[82:83], v[132:133], v[82:83] op_sel_hi:[0,1]
	v_pk_fma_f32 v[82:83], v[66:67], v[134:135], v[82:83] op_sel_hi:[1,0,1] neg_lo:[0,0,1] neg_hi:[0,0,1]
	v_pk_mul_f32 v[66:67], v[130:131], v[182:183] op_sel_hi:[0,1]
	v_pk_fma_f32 v[66:67], v[80:81], v[128:129], v[66:67] op_sel_hi:[1,0,1]
	v_pk_mul_f32 v[102:103], v[130:131], v[190:191] op_sel_hi:[0,1]
	v_pk_mul_f32 v[66:67], v[132:133], v[66:67] op_sel_hi:[0,1]
	v_pk_fma_f32 v[106:107], v[64:65], v[134:135], v[66:67] op_sel_hi:[1,0,1] neg_lo:[0,0,1] neg_hi:[0,0,1]
	v_pk_mul_f32 v[64:65], v[130:131], v[180:181] op_sel_hi:[0,1]
	v_pk_fma_f32 v[64:65], v[86:87], v[128:129], v[64:65] op_sel_hi:[1,0,1]
	v_pk_fma_f32 v[96:97], v[118:119], v[134:135], v[96:97] op_sel_hi:[1,0,1] neg_lo:[0,0,1] neg_hi:[0,0,1]
	v_pk_mul_f32 v[64:65], v[132:133], v[64:65] op_sel_hi:[0,1]
	v_pk_fma_f32 v[70:71], v[70:71], v[134:135], v[64:65] op_sel_hi:[1,0,1] neg_lo:[0,0,1] neg_hi:[0,0,1]
	v_pk_mul_f32 v[64:65], v[130:131], v[178:179] op_sel_hi:[0,1]
	v_pk_fma_f32 v[64:65], v[84:85], v[128:129], v[64:65] op_sel_hi:[1,0,1]
	v_pk_fma_f32 v[102:103], v[104:105], v[128:129], v[102:103] op_sel_hi:[1,0,1]
	v_pk_mul_f32 v[64:65], v[132:133], v[64:65] op_sel_hi:[0,1]
	v_pk_fma_f32 v[80:81], v[68:69], v[134:135], v[64:65] op_sel_hi:[1,0,1] neg_lo:[0,0,1] neg_hi:[0,0,1]
	v_pk_mul_f32 v[64:65], v[130:131], v[176:177] op_sel_hi:[0,1]
	v_pk_fma_f32 v[64:65], v[90:91], v[128:129], v[64:65] op_sel_hi:[1,0,1]
	v_pk_mul_f32 v[68:69], v[130:131], v[170:171] op_sel_hi:[0,1]
	v_pk_mul_f32 v[64:65], v[132:133], v[64:65] op_sel_hi:[0,1]
	v_pk_fma_f32 v[66:67], v[74:75], v[134:135], v[64:65] op_sel_hi:[1,0,1] neg_lo:[0,0,1] neg_hi:[0,0,1]
	v_pk_mul_f32 v[64:65], v[130:131], v[174:175] op_sel_hi:[0,1]
	v_pk_fma_f32 v[64:65], v[88:89], v[128:129], v[64:65] op_sel_hi:[1,0,1]
	v_pk_fma_f32 v[68:69], v[92:93], v[128:129], v[68:69] op_sel_hi:[1,0,1]
	v_pk_mul_f32 v[64:65], v[132:133], v[64:65] op_sel_hi:[0,1]
	v_pk_mul_f32 v[68:69], v[132:133], v[68:69] op_sel_hi:[0,1]
	v_pk_fma_f32 v[74:75], v[72:73], v[134:135], v[64:65] op_sel_hi:[1,0,1] neg_lo:[0,0,1] neg_hi:[0,0,1]
	v_pk_fma_f32 v[72:73], v[76:77], v[134:135], v[68:69] op_sel_hi:[1,0,1] neg_lo:[0,0,1] neg_hi:[0,0,1]
	v_pk_mul_f32 v[68:69], v[130:131], v[166:167] op_sel_hi:[0,1]
	v_pk_fma_f32 v[50:51], v[50:51], v[128:129], v[68:69] op_sel_hi:[1,0,1]
	v_pk_mul_f32 v[118:119], v[96:97], v[96:97]
	v_pk_mul_f32 v[50:51], v[132:133], v[50:51] op_sel_hi:[0,1]
	v_pk_fma_f32 v[50:51], v[34:35], v[134:135], v[50:51] op_sel_hi:[1,0,1] neg_lo:[0,0,1] neg_hi:[0,0,1]
	v_pk_mul_f32 v[34:35], v[130:131], v[164:165] op_sel_hi:[0,1]
	v_pk_fma_f32 v[34:35], v[48:49], v[128:129], v[34:35] op_sel_hi:[1,0,1]
	v_pk_mul_f32 v[102:103], v[132:133], v[102:103] op_sel_hi:[0,1]
	v_pk_mul_f32 v[34:35], v[132:133], v[34:35] op_sel_hi:[0,1]
	v_pk_fma_f32 v[68:69], v[32:33], v[134:135], v[34:35] op_sel_hi:[1,0,1] neg_lo:[0,0,1] neg_hi:[0,0,1]
	v_pk_mul_f32 v[32:33], v[130:131], v[162:163] op_sel_hi:[0,1]
	v_pk_fma_f32 v[32:33], v[54:55], v[128:129], v[32:33] op_sel_hi:[1,0,1]
	v_pk_fma_f32 v[104:105], v[120:121], v[134:135], v[102:103] op_sel_hi:[1,0,1] neg_lo:[0,0,1] neg_hi:[0,0,1]
	v_pk_mul_f32 v[32:33], v[132:133], v[32:33] op_sel_hi:[0,1]
	v_pk_fma_f32 v[38:39], v[38:39], v[134:135], v[32:33] op_sel_hi:[1,0,1] neg_lo:[0,0,1] neg_hi:[0,0,1]
	v_pk_mul_f32 v[32:33], v[130:131], v[160:161] op_sel_hi:[0,1]
	v_pk_fma_f32 v[32:33], v[52:53], v[128:129], v[32:33] op_sel_hi:[1,0,1]
	v_pk_mul_f32 v[100:101], v[132:133], v[100:101] op_sel_hi:[0,1]
	v_pk_mul_f32 v[32:33], v[132:133], v[32:33] op_sel_hi:[0,1]
	v_pk_fma_f32 v[48:49], v[36:37], v[134:135], v[32:33] op_sel_hi:[1,0,1] neg_lo:[0,0,1] neg_hi:[0,0,1]
	v_pk_mul_f32 v[32:33], v[130:131], v[158:159] op_sel_hi:[0,1]
	v_pk_fma_f32 v[32:33], v[58:59], v[128:129], v[32:33] op_sel_hi:[1,0,1]
	v_pk_mul_f32 v[58:59], v[130:131], v[150:151] op_sel_hi:[0,1]
	v_pk_fma_f32 v[18:19], v[18:19], v[128:129], v[58:59] op_sel_hi:[1,0,1]
	v_pk_mul_f32 v[120:121], v[104:105], v[104:105]
	v_pk_mul_f32 v[18:19], v[132:133], v[18:19] op_sel_hi:[0,1]
	v_pk_fma_f32 v[18:19], v[2:3], v[134:135], v[18:19] op_sel_hi:[1,0,1] neg_lo:[0,0,1] neg_hi:[0,0,1]
	v_pk_mul_f32 v[2:3], v[130:131], v[146:147] op_sel_hi:[0,1]
	v_pk_fma_f32 v[2:3], v[16:17], v[128:129], v[2:3] op_sel_hi:[1,0,1]
	v_pk_fma_f32 v[100:101], v[122:123], v[134:135], v[100:101] op_sel_hi:[1,0,1] neg_lo:[0,0,1] neg_hi:[0,0,1]
	v_pk_mul_f32 v[2:3], v[132:133], v[2:3] op_sel_hi:[0,1]
	v_pk_fma_f32 v[16:17], v[0:1], v[134:135], v[2:3] op_sel_hi:[1,0,1] neg_lo:[0,0,1] neg_hi:[0,0,1]
	v_pk_mul_f32 v[0:1], v[130:131], v[142:143] op_sel_hi:[0,1]
	v_pk_fma_f32 v[0:1], v[22:23], v[128:129], v[0:1] op_sel_hi:[1,0,1]
	v_add_f32_e32 v22, v208, v209
	v_add_f32_e32 v22, v22, v200
	v_add_f32_e32 v22, v22, v201
	v_add_f32_e32 v22, v22, v116
	v_add_f32_e32 v22, v22, v117
	v_add_f32_e32 v22, v22, v118
	v_add_f32_e32 v22, v22, v119
	v_add_f32_e32 v22, v22, v120
	v_pk_mul_f32 v[122:123], v[100:101], v[100:101]
	v_pk_mul_f32 v[102:103], v[130:131], v[188:189] op_sel_hi:[0,1]
	v_add_f32_e32 v22, v22, v121
	v_pk_fma_f32 v[102:103], v[110:111], v[128:129], v[102:103] op_sel_hi:[1,0,1]
	v_add_f32_e32 v22, v22, v122
	v_pk_mul_f32 v[102:103], v[132:133], v[102:103] op_sel_hi:[0,1]
	v_pk_mul_f32 v[124:125], v[108:109], v[108:109]
	v_add_f32_e32 v22, v22, v123
	v_pk_fma_f32 v[102:103], v[126:127], v[134:135], v[102:103] op_sel_hi:[1,0,1] neg_lo:[0,0,1] neg_hi:[0,0,1]
	v_add_f32_e32 v22, v22, v124
	v_pk_mul_f32 v[110:111], v[102:103], v[102:103]
	v_add_f32_e32 v22, v22, v125
	v_add_f32_e32 v22, v22, v110
	v_pk_mul_f32 v[182:183], v[106:107], v[106:107]
	v_add_f32_e32 v22, v22, v111
	v_add_f32_e32 v22, v22, v182
	v_pk_mul_f32 v[126:127], v[82:83], v[82:83]
	v_add_f32_e32 v22, v22, v183
	v_add_f32_e32 v22, v22, v126
	v_lshl_add_u64 v[10:11], s[14:15], 1, v[10:11]
	v_pk_mul_f32 v[84:85], v[80:81], v[80:81]
	v_add_f32_e32 v22, v22, v127
	v_lshl_add_u64 v[148:149], v[10:11], 0, v[12:13]
	global_load_dwordx4 v[10:13], v192, s[16:17]
	global_load_dwordx4 v[116:119], v192, s[16:17] offset:32
	global_load_dwordx4 v[120:123], v192, s[16:17] offset:64
	global_load_dwordx4 v[124:127], v192, s[16:17] offset:96
	global_load_dwordx4 v[160:163], v192, s[16:17] offset:128
	global_load_dwordx4 v[164:167], v192, s[16:17] offset:160
	global_load_dwordx4 v[176:179], v192, s[16:17] offset:192
	global_load_dwordx4 v[180:183], v192, s[16:17] offset:224
	global_load_dwordx4 v[184:187], v192, s[16:17] offset:256
	global_load_dwordx4 v[188:191], v192, s[16:17] offset:288
	global_load_dwordx4 v[200:203], v192, s[16:17] offset:320
	global_load_dwordx4 v[204:207], v192, s[16:17] offset:352
	global_load_dwordx4 v[208:211], v192, s[16:17] offset:384
	global_load_dwordx4 v[240:243], v192, s[16:17] offset:416
	global_load_dwordx4 v[244:247], v192, s[16:17] offset:448
	global_load_dwordx4 v[248:251], v192, s[16:17] offset:480
	v_add_f32_e32 v22, v22, v84
	v_pk_mul_f32 v[86:87], v[70:71], v[70:71]
	v_add_f32_e32 v22, v22, v85
	v_add_f32_e32 v22, v22, v86
	v_pk_mul_f32 v[88:89], v[74:75], v[74:75]
	v_add_f32_e32 v22, v22, v87
	v_add_f32_e32 v22, v22, v88
	v_pk_mul_f32 v[90:91], v[66:67], v[66:67]
	v_pk_mul_f32 v[64:65], v[130:131], v[172:173] op_sel_hi:[0,1]
	v_add_f32_e32 v22, v22, v89
	v_pk_fma_f32 v[64:65], v[94:95], v[128:129], v[64:65] op_sel_hi:[1,0,1]
	v_add_f32_e32 v22, v22, v90
	v_pk_mul_f32 v[64:65], v[132:133], v[64:65] op_sel_hi:[0,1]
	v_pk_mul_f32 v[76:77], v[72:73], v[72:73]
	v_add_f32_e32 v22, v22, v91
	v_pk_fma_f32 v[64:65], v[78:79], v[134:135], v[64:65] op_sel_hi:[1,0,1] neg_lo:[0,0,1] neg_hi:[0,0,1]
	v_add_f32_e32 v22, v22, v76
	v_pk_mul_f32 v[78:79], v[64:65], v[64:65]
	v_add_f32_e32 v22, v22, v77
	v_add_f32_e32 v22, v22, v78
	v_pk_mul_f32 v[94:95], v[68:69], v[68:69]
	v_add_f32_e32 v22, v22, v79
	v_add_f32_e32 v22, v22, v94
	v_pk_mul_f32 v[92:93], v[50:51], v[50:51]
	v_add_f32_e32 v22, v22, v95
	v_pk_mul_f32 v[32:33], v[132:133], v[32:33] op_sel_hi:[0,1]
	v_add_f32_e32 v22, v22, v92
	v_pk_mul_f32 v[52:53], v[48:49], v[48:49]
	v_pk_fma_f32 v[34:35], v[42:43], v[134:135], v[32:33] op_sel_hi:[1,0,1] neg_lo:[0,0,1] neg_hi:[0,0,1]
	v_pk_mul_f32 v[32:33], v[130:131], v[156:157] op_sel_hi:[0,1]
	v_add_f32_e32 v22, v22, v93
	v_pk_fma_f32 v[32:33], v[56:57], v[128:129], v[32:33] op_sel_hi:[1,0,1]
	v_add_f32_e32 v22, v22, v52
	v_pk_mul_f32 v[54:55], v[38:39], v[38:39]
	v_pk_mul_f32 v[32:33], v[132:133], v[32:33] op_sel_hi:[0,1]
	v_add_f32_e32 v22, v22, v53
	v_pk_fma_f32 v[40:41], v[40:41], v[134:135], v[32:33] op_sel_hi:[1,0,1] neg_lo:[0,0,1] neg_hi:[0,0,1]
	v_add_f32_e32 v22, v22, v54
	v_pk_mul_f32 v[56:57], v[40:41], v[40:41]
	v_pk_mul_f32 v[36:37], v[130:131], v[152:153] op_sel_hi:[0,1]
	v_add_f32_e32 v22, v22, v55
	v_pk_fma_f32 v[36:37], v[60:61], v[128:129], v[36:37] op_sel_hi:[1,0,1]
	v_add_f32_e32 v22, v22, v56
	v_pk_mul_f32 v[42:43], v[34:35], v[34:35]
	v_pk_mul_f32 v[32:33], v[130:131], v[154:155] op_sel_hi:[0,1]
	v_pk_mul_f32 v[36:37], v[132:133], v[36:37] op_sel_hi:[0,1]
	v_add_f32_e32 v22, v22, v57
	v_pk_fma_f32 v[32:33], v[62:63], v[128:129], v[32:33] op_sel_hi:[1,0,1]
	v_pk_fma_f32 v[36:37], v[44:45], v[134:135], v[36:37] op_sel_hi:[1,0,1] neg_lo:[0,0,1] neg_hi:[0,0,1]
	v_add_f32_e32 v22, v22, v42
	v_pk_mul_f32 v[32:33], v[132:133], v[32:33] op_sel_hi:[0,1]
	v_pk_mul_f32 v[44:45], v[36:37], v[36:37]
	v_add_f32_e32 v22, v22, v43
	v_pk_fma_f32 v[32:33], v[46:47], v[134:135], v[32:33] op_sel_hi:[1,0,1] neg_lo:[0,0,1] neg_hi:[0,0,1]
	v_add_f32_e32 v22, v22, v44
	v_pk_mul_f32 v[46:47], v[32:33], v[32:33]
	v_add_f32_e32 v22, v22, v45
	v_add_f32_e32 v22, v22, v46
	v_pk_mul_f32 v[60:61], v[16:17], v[16:17]
	v_pk_mul_f32 v[2:3], v[130:131], v[140:141] op_sel_hi:[0,1]
	v_add_f32_e32 v22, v22, v47
	v_pk_fma_f32 v[2:3], v[20:21], v[128:129], v[2:3] op_sel_hi:[1,0,1]
	v_add_f32_e32 v22, v22, v60
	v_pk_mul_f32 v[58:59], v[18:19], v[18:19]
	v_pk_mul_f32 v[2:3], v[132:133], v[2:3] op_sel_hi:[0,1]
	v_add_f32_e32 v22, v22, v61
	v_pk_fma_f32 v[4:5], v[4:5], v[134:135], v[2:3] op_sel_hi:[1,0,1] neg_lo:[0,0,1] neg_hi:[0,0,1]
	v_add_f32_e32 v22, v22, v58
	v_pk_mul_f32 v[0:1], v[132:133], v[0:1] op_sel_hi:[0,1]
	v_pk_mul_f32 v[20:21], v[4:5], v[4:5]
	v_pk_mul_f32 v[2:3], v[130:131], v[138:139] op_sel_hi:[0,1]
	v_add_f32_e32 v22, v22, v59
	v_pk_fma_f32 v[0:1], v[6:7], v[134:135], v[0:1] op_sel_hi:[1,0,1] neg_lo:[0,0,1] neg_hi:[0,0,1]
	v_pk_fma_f32 v[2:3], v[24:25], v[128:129], v[2:3] op_sel_hi:[1,0,1]
	v_add_f32_e32 v20, v22, v20
	v_pk_mul_f32 v[6:7], v[0:1], v[0:1]
	v_pk_mul_f32 v[2:3], v[132:133], v[2:3] op_sel_hi:[0,1]
	v_add_f32_e32 v20, v20, v21
	v_pk_fma_f32 v[2:3], v[8:9], v[134:135], v[2:3] op_sel_hi:[1,0,1] neg_lo:[0,0,1] neg_hi:[0,0,1]
	v_add_f32_e32 v6, v20, v6
	v_pk_mul_f32 v[8:9], v[2:3], v[2:3]
	v_add_f32_e32 v6, v6, v7
	v_add_f32_e32 v6, v6, v8
	v_add_f32_e32 v6, v6, v9
	v_add_f32_e32 v6, v6, v136
	v_add_f32_e32 v6, v6, v137
	v_add_f32_e32 v6, v6, v144
	v_pk_mul_f32 v[168:169], v[30:31], v[30:31]
	v_add_f32_e32 v6, v6, v145
	v_add_f32_e32 v6, v6, v168
	v_add_f32_e32 v6, v6, v169
	ds_bpermute_b32 v7, v235, v6
	v_lshl_add_u64 v[14:15], v[148:149], 0, s[10:11]
	s_waitcnt lgkmcnt(0)
	v_add_f32_e32 v6, v6, v7
	v_fmamk_f32 v6, v6, 0x3c000000, v219
	v_cmp_gt_f32_e32 vcc, s4, v6
	v_mul_f32_e32 v7, 0x4f800000, v6
	s_mov_b32 s4, 0x1fa00000
	v_cndmask_b32_e32 v6, v6, v7, vcc
	v_sqrt_f32_e32 v7, v6
	s_nop 0
	v_add_u32_e32 v8, -1, v7
	v_fma_f32 v9, -v8, v7, v6
	v_cmp_ge_f32_e64 s[10:11], 0, v9
	v_add_u32_e32 v9, 1, v7
	s_nop 0
	v_cndmask_b32_e64 v8, v7, v8, s[10:11]
	v_fma_f32 v7, -v9, v7, v6
	v_cmp_lt_f32_e64 s[10:11], 0, v7
	s_nop 1
	v_cndmask_b32_e64 v7, v8, v9, s[10:11]
	v_mul_f32_e32 v8, 0x37800000, v7
	v_cndmask_b32_e32 v7, v7, v8, vcc
	v_cmp_class_f32_e32 vcc, v6, v220
	s_nop 1
	v_cndmask_b32_e32 v6, v7, v6, vcc
	v_div_scale_f32 v7, s[10:11], v6, v6, v238
	v_rcp_f32_e32 v8, v7
	s_nop 0
	v_fma_f32 v9, -v7, v8, 1.0
	v_fmac_f32_e32 v8, v9, v8
	v_div_scale_f32 v9, vcc, v238, v6, v238
	v_mul_f32_e32 v20, v9, v8
	v_fma_f32 v21, -v7, v20, v9
	v_fmac_f32_e32 v20, v21, v8
	v_fma_f32 v7, -v7, v20, v9
	v_div_fmas_f32 v7, v7, v8, v20
	v_div_fixup_f32 v6, v7, v6, v238
	v_pk_mul_f32 v[8:9], v[112:113], v[6:7] op_sel_hi:[1,0]
	v_pk_mul_f32 v[4:5], v[4:5], v[6:7] op_sel_hi:[1,0]
	s_waitcnt vmcnt(0)
	v_pk_mul_f32 v[8:9], v[10:11], v[8:9]
	v_pk_mul_f32 v[10:11], v[98:99], v[6:7] op_sel_hi:[1,0]
	v_cvt_pk_bf16_f32 v8, v8, v9
	v_pk_mul_f32 v[10:11], v[12:13], v[10:11]
	v_pk_mul_f32 v[12:13], v[114:115], v[6:7] op_sel_hi:[1,0]
	v_cvt_pk_bf16_f32 v9, v10, v11
	v_add_co_u32_e32 v10, vcc, s4, v148
	v_pk_mul_f32 v[0:1], v[0:1], v[6:7] op_sel_hi:[1,0]
	s_nop 0
	v_addc_co_u32_e32 v11, vcc, 0, v149, vcc
	global_store_dwordx2 v[10:11], v[8:9], off offset:2560
	s_nop 1
	v_mov_b64_e32 v[8:9], v[116:117]
	v_mov_b64_e32 v[10:11], v[118:119]
	v_pk_mul_f32 v[8:9], v[8:9], v[12:13]
	v_pk_mul_f32 v[12:13], v[96:97], v[6:7] op_sel_hi:[1,0]
	v_cvt_pk_bf16_f32 v8, v8, v9
	v_pk_mul_f32 v[10:11], v[10:11], v[12:13]
	v_pk_mul_f32 v[12:13], v[104:105], v[6:7] op_sel_hi:[1,0]
	v_cvt_pk_bf16_f32 v9, v10, v11
	global_store_dwordx2 v[14:15], v[8:9], off offset:16
	s_nop 1
	v_mov_b64_e32 v[8:9], v[120:121]
	v_mov_b64_e32 v[10:11], v[122:123]
	v_pk_mul_f32 v[8:9], v[8:9], v[12:13]
	v_pk_mul_f32 v[12:13], v[100:101], v[6:7] op_sel_hi:[1,0]
	v_cvt_pk_bf16_f32 v8, v8, v9
	v_pk_mul_f32 v[10:11], v[10:11], v[12:13]
	v_pk_mul_f32 v[12:13], v[108:109], v[6:7] op_sel_hi:[1,0]
	v_cvt_pk_bf16_f32 v9, v10, v11
	global_store_dwordx2 v[14:15], v[8:9], off offset:32
	s_nop 1
	v_mov_b64_e32 v[8:9], v[124:125]
	v_mov_b64_e32 v[10:11], v[126:127]
	v_pk_mul_f32 v[8:9], v[8:9], v[12:13]
	v_pk_mul_f32 v[12:13], v[102:103], v[6:7] op_sel_hi:[1,0]
	v_cvt_pk_bf16_f32 v8, v8, v9
	v_pk_mul_f32 v[10:11], v[10:11], v[12:13]
	v_pk_mul_f32 v[12:13], v[106:107], v[6:7] op_sel_hi:[1,0]
	v_cvt_pk_bf16_f32 v9, v10, v11
	global_store_dwordx2 v[14:15], v[8:9], off offset:48
	s_nop 1
	v_mov_b64_e32 v[8:9], v[160:161]
	v_mov_b64_e32 v[10:11], v[162:163]
	v_pk_mul_f32 v[8:9], v[8:9], v[12:13]
	v_pk_mul_f32 v[12:13], v[82:83], v[6:7] op_sel_hi:[1,0]
	v_cvt_pk_bf16_f32 v8, v8, v9
	v_pk_mul_f32 v[10:11], v[10:11], v[12:13]
	v_pk_mul_f32 v[12:13], v[80:81], v[6:7] op_sel_hi:[1,0]
	v_cvt_pk_bf16_f32 v9, v10, v11
	global_store_dwordx2 v[14:15], v[8:9], off offset:64
	s_nop 1
	v_mov_b64_e32 v[8:9], v[164:165]
	v_mov_b64_e32 v[10:11], v[166:167]
	v_pk_mul_f32 v[8:9], v[8:9], v[12:13]
	v_pk_mul_f32 v[12:13], v[70:71], v[6:7] op_sel_hi:[1,0]
	v_cvt_pk_bf16_f32 v8, v8, v9
	v_pk_mul_f32 v[10:11], v[10:11], v[12:13]
	v_pk_mul_f32 v[12:13], v[74:75], v[6:7] op_sel_hi:[1,0]
	v_cvt_pk_bf16_f32 v9, v10, v11
	global_store_dwordx2 v[14:15], v[8:9], off offset:80
	s_nop 1
	v_mov_b64_e32 v[8:9], v[176:177]
	v_mov_b64_e32 v[10:11], v[178:179]
	v_pk_mul_f32 v[8:9], v[12:13], v[8:9]
	v_pk_mul_f32 v[12:13], v[66:67], v[6:7] op_sel_hi:[1,0]
	v_cvt_pk_bf16_f32 v8, v8, v9
	v_pk_mul_f32 v[10:11], v[12:13], v[10:11]
	v_pk_mul_f32 v[12:13], v[72:73], v[6:7] op_sel_hi:[1,0]
	v_cvt_pk_bf16_f32 v9, v10, v11
	global_store_dwordx2 v[14:15], v[8:9], off offset:96
	s_nop 1
	v_mov_b64_e32 v[8:9], v[180:181]
	v_mov_b64_e32 v[10:11], v[182:183]
	v_pk_mul_f32 v[8:9], v[12:13], v[8:9]
	v_pk_mul_f32 v[12:13], v[64:65], v[6:7] op_sel_hi:[1,0]
	v_cvt_pk_bf16_f32 v8, v8, v9
	v_pk_mul_f32 v[10:11], v[12:13], v[10:11]
	v_pk_mul_f32 v[12:13], v[68:69], v[6:7] op_sel_hi:[1,0]
	v_cvt_pk_bf16_f32 v9, v10, v11
	global_store_dwordx2 v[14:15], v[8:9], off offset:112
	s_nop 1
	v_mov_b64_e32 v[8:9], v[184:185]
	v_mov_b64_e32 v[10:11], v[186:187]
	v_pk_mul_f32 v[8:9], v[12:13], v[8:9]
	v_pk_mul_f32 v[12:13], v[50:51], v[6:7] op_sel_hi:[1,0]
	v_cvt_pk_bf16_f32 v8, v8, v9
	v_pk_mul_f32 v[10:11], v[12:13], v[10:11]
	v_pk_mul_f32 v[12:13], v[48:49], v[6:7] op_sel_hi:[1,0]
	v_cvt_pk_bf16_f32 v9, v10, v11
	global_store_dwordx2 v[14:15], v[8:9], off offset:128
	s_nop 1
	v_mov_b64_e32 v[8:9], v[188:189]
	v_mov_b64_e32 v[10:11], v[190:191]
	v_pk_mul_f32 v[8:9], v[12:13], v[8:9]
	v_pk_mul_f32 v[12:13], v[38:39], v[6:7] op_sel_hi:[1,0]
	v_cvt_pk_bf16_f32 v8, v8, v9
	v_pk_mul_f32 v[10:11], v[12:13], v[10:11]
	v_pk_mul_f32 v[12:13], v[40:41], v[6:7] op_sel_hi:[1,0]
	v_cvt_pk_bf16_f32 v9, v10, v11
	global_store_dwordx2 v[14:15], v[8:9], off offset:144
	s_nop 1
	v_mov_b64_e32 v[8:9], v[200:201]
	v_mov_b64_e32 v[10:11], v[202:203]
	v_pk_mul_f32 v[8:9], v[12:13], v[8:9]
	v_pk_mul_f32 v[12:13], v[34:35], v[6:7] op_sel_hi:[1,0]
	v_cvt_pk_bf16_f32 v8, v8, v9
	v_pk_mul_f32 v[10:11], v[12:13], v[10:11]
	v_pk_mul_f32 v[12:13], v[36:37], v[6:7] op_sel_hi:[1,0]
	v_cvt_pk_bf16_f32 v9, v10, v11
	global_store_dwordx2 v[14:15], v[8:9], off offset:160
	s_nop 1
	v_mov_b64_e32 v[8:9], v[204:205]
	v_mov_b64_e32 v[10:11], v[206:207]
	v_pk_mul_f32 v[8:9], v[12:13], v[8:9]
	v_pk_mul_f32 v[12:13], v[32:33], v[6:7] op_sel_hi:[1,0]
	v_cvt_pk_bf16_f32 v8, v8, v9
	v_pk_mul_f32 v[10:11], v[12:13], v[10:11]
	v_pk_mul_f32 v[12:13], v[16:17], v[6:7] op_sel_hi:[1,0]
	v_cvt_pk_bf16_f32 v9, v10, v11
	global_store_dwordx2 v[14:15], v[8:9], off offset:176
	s_nop 1
	v_mov_b64_e32 v[8:9], v[208:209]
	v_mov_b64_e32 v[10:11], v[210:211]
	v_pk_mul_f32 v[8:9], v[12:13], v[8:9]
	v_pk_mul_f32 v[12:13], v[18:19], v[6:7] op_sel_hi:[1,0]
	v_cvt_pk_bf16_f32 v8, v8, v9
	v_pk_mul_f32 v[10:11], v[12:13], v[10:11]
	s_nop 0
	v_cvt_pk_bf16_f32 v9, v10, v11
	global_store_dwordx2 v[14:15], v[8:9], off offset:192
	s_nop 1
	v_mov_b64_e32 v[8:9], v[240:241]
	v_mov_b64_e32 v[10:11], v[242:243]
	v_pk_mul_f32 v[4:5], v[4:5], v[8:9]
	v_pk_mul_f32 v[0:1], v[0:1], v[10:11]
	v_cvt_pk_bf16_f32 v4, v4, v5
	v_cvt_pk_bf16_f32 v5, v0, v1
	global_store_dwordx2 v[14:15], v[4:5], off offset:208
	s_nop 1
	v_mov_b64_e32 v[8:9], v[244:245]
	v_mov_b64_e32 v[10:11], v[246:247]
	v_pk_mul_f32 v[0:1], v[2:3], v[6:7] op_sel_hi:[1,0]
	v_pk_mul_f32 v[2:3], v[26:27], v[6:7] op_sel_hi:[1,0]
	v_pk_mul_f32 v[4:5], v[28:29], v[6:7] op_sel_hi:[1,0]
	v_pk_mul_f32 v[0:1], v[0:1], v[8:9]
	v_pk_mul_f32 v[2:3], v[2:3], v[10:11]
	v_cvt_pk_bf16_f32 v0, v0, v1
	v_cvt_pk_bf16_f32 v1, v2, v3
	global_store_dwordx2 v[14:15], v[0:1], off offset:224
	s_nop 1
	v_mov_b64_e32 v[0:1], v[248:249]
	v_mov_b64_e32 v[2:3], v[250:251]
	v_pk_mul_f32 v[0:1], v[4:5], v[0:1]
	v_pk_mul_f32 v[4:5], v[30:31], v[6:7] op_sel_hi:[1,0]
	v_cvt_pk_bf16_f32 v0, v0, v1
	v_pk_mul_f32 v[2:3], v[4:5], v[2:3]
	s_nop 0
	v_cvt_pk_bf16_f32 v1, v2, v3
	global_store_dwordx2 v[14:15], v[0:1], off offset:240
